# plus MLA attention loop: K/V fragment LDS reads batched ahead of MFMAs; EpiRes (WOUT/XO/FFN2) xb loads hoisted in two batches
# baseline (speedup 1.0000x reference)
; __device__ __forceinline__ u32x4 pk8(f32x4 a, f32x4 b) { u32x4 w; w.x = pk2(a.x, a.y); w.y = pk2(a.z, a.w); w.z = pk2(b.x, b.y); w.w = pk2(b.z, b.w); return w; }
; template <int DQK, int DV, bool CAUSAL, bool MLA> ...
;     ...
;         float mx = -INFINITY;
; #pragma unroll
;         for (int k4 = 0; k4 < 4; ++k4) mx = fmaxf(mx, fmaxf(fmaxf(sT[k4][0], sT[k4][1]), fmaxf(sT[k4][2], sT[k4][3])));
;         mx = fmaxf(mx, __shfl_xor(mx, 16)); mx = fmaxf(mx, __shfl_xor(mx, 32));
;         const float mnew = fmaxf(mrun, mx); const float alpha = __builtin_amdgcn_exp2f(mrun - mnew); mrun = mnew;
;         float psum = 0.f;
; #pragma unroll
;         for (int k4 = 0; k4 < 4; ++k4)
; #pragma unroll
;             for (int r = 0; r < 4; ++r) { const float pv = __builtin_amdgcn_exp2f(sT[k4][r] - mnew); sT[k4][r] = pv; psum += pv; }
;         lsum = lsum * alpha + psum;
; #pragma unroll
;         for (int d = 0; d < NDT; ++d) oT[d] *= alpha;
; #pragma unroll
;         for (int kc = 0; kc < 2; ++kc) {
;             const bf16x8 pb = __builtin_bit_cast(bf16x8, pk8(sT[2 * kc], sT[2 * kc + 1]));
; #pragma unroll
;             for (int d = 0; d < NDT; ++d) { const unsigned char* vp = Vs + (16 * d + j) * VS + (32 * kc + 4 * g) * 2;
;                 const u32x2 lo = *(const u32x2*)vp, hi = *(const u32x2*)(vp + 32); u32x4 w; w.x = lo.x; w.y = lo.y; w.z = hi.x; w.w = hi.y;
;                 oT[d] = __builtin_amdgcn_mfma_f32_16x16x32_bf16(__builtin_bit_cast(bf16x8, w), pb, oT[d], 0, 0, 0); }
;         }
.LBB0_1430:
	s_or_b64 exec, exec, s[16:17]
	v_max_f32_e32 v82, v47, v47
	v_max_f32_e32 v83, v46, v46
	v_max_f32_e32 v82, v83, v82
	v_max_f32_e32 v83, v55, v55
	v_max_f32_e32 v84, v54, v54
	v_max_f32_e32 v83, v84, v83
	v_max3_f32 v82, v44, v45, v82
	v_max3_f32 v83, v52, v53, v83
	s_mov_b32 s0, 0xff800000
	v_max3_f32 v82, v82, s0, v83
	v_max_f32_e32 v83, v43, v43
	v_max_f32_e32 v84, v42, v42
	v_max_f32_e32 v83, v84, v83
	v_max_f32_e32 v84, v51, v51
	v_max_f32_e32 v85, v50, v50
	v_max_f32_e32 v84, v85, v84
	v_max3_f32 v83, v40, v41, v83
	v_max3_f32 v84, v48, v49, v84
	v_max3_f32 v82, v82, v83, v84
	ds_bpermute_b32 v83, v138, v82
	s_waitcnt lgkmcnt(0)
	v_max_f32_e32 v83, v83, v83
	v_max_f32_e32 v82, v82, v83
	ds_bpermute_b32 v83, v139, v82
	s_waitcnt lgkmcnt(0)
	v_max3_f32 v82, v81, v82, v83
	v_sub_f32_e32 v44, v44, v82
	v_exp_f32_e32 v44, v44
	v_sub_f32_e32 v45, v45, v82
	v_exp_f32_e32 v45, v45
	v_sub_f32_e32 v46, v46, v82
	v_exp_f32_e32 v46, v46
	v_sub_f32_e32 v47, v47, v82
	v_exp_f32_e32 v47, v47
	v_sub_f32_e32 v52, v52, v82
	v_add_f32_e32 v83, 0, v44
	v_exp_f32_e32 v52, v52
	v_sub_f32_e32 v53, v53, v82
	v_add_f32_e32 v83, v45, v83
	v_exp_f32_e32 v53, v53
	v_sub_f32_e32 v54, v54, v82
	v_add_f32_e32 v83, v46, v83
	v_exp_f32_e32 v54, v54
	v_sub_f32_e32 v55, v55, v82
	v_add_f32_e32 v83, v47, v83
	v_exp_f32_e32 v55, v55
	v_sub_f32_e32 v40, v40, v82
	v_add_f32_e32 v83, v52, v83
	v_exp_f32_e32 v84, v40
	v_add_f32_e32 v83, v53, v83
	v_add_f32_e32 v83, v54, v83
	v_sub_f32_e32 v41, v41, v82
	v_add_f32_e32 v83, v55, v83
	v_exp_f32_e32 v41, v41
	v_sub_f32_e32 v42, v42, v82
	v_add_f32_e32 v40, v84, v83
	v_exp_f32_e32 v83, v42
	v_sub_f32_e32 v42, v43, v82
	v_exp_f32_e32 v85, v42
	v_add_f32_e32 v40, v41, v40
	v_add_f32_e32 v40, v83, v40
	v_cvt_pk_bf16_f32 v43, v46, v47
	v_add_f32_e32 v42, v85, v40
	v_sub_f32_e32 v40, v48, v82
	v_exp_f32_e32 v86, v40
	v_sub_f32_e32 v40, v49, v82
	v_exp_f32_e32 v87, v40
	v_sub_f32_e32 v40, v50, v82
	v_exp_f32_e32 v50, v40
	v_sub_f32_e32 v40, v51, v82
	v_exp_f32_e32 v51, v40
	v_add_f32_e32 v42, v86, v42
	v_add_f32_e32 v42, v87, v42
	v_add_f32_e32 v42, v50, v42
	v_add_f32_e32 v88, v51, v42
	v_cvt_pk_bf16_f32 v42, v44, v45
	v_cvt_pk_bf16_f32 v44, v52, v53
	v_sub_f32_e32 v81, v81, v82
	v_exp_f32_e32 v40, v81
	v_cvt_pk_bf16_f32 v45, v54, v55
	v_pk_mul_f32 v[10:11], v[10:11], v[40:41] op_sel_hi:[1,0]
	v_pk_mul_f32 v[8:9], v[8:9], v[40:41] op_sel_hi:[1,0]
	v_pk_mul_f32 v[14:15], v[14:15], v[40:41] op_sel_hi:[1,0]
	v_pk_mul_f32 v[12:13], v[12:13], v[40:41] op_sel_hi:[1,0]
	s_waitcnt lgkmcnt(0)
	v_mfma_f32_16x16x32_bf16 v[8:11], v[188:191], v[42:45], v[8:11]
	v_pk_mul_f32 v[18:19], v[18:19], v[40:41] op_sel_hi:[1,0]
	v_pk_mul_f32 v[16:17], v[16:17], v[40:41] op_sel_hi:[1,0]
	s_waitcnt lgkmcnt(0)
	v_mfma_f32_16x16x32_bf16 v[12:15], v[192:195], v[42:45], v[12:15]
	v_pk_mul_f32 v[22:23], v[22:23], v[40:41] op_sel_hi:[1,0]
	s_waitcnt lgkmcnt(0)
	v_mfma_f32_16x16x32_bf16 v[16:19], v[196:199], v[42:45], v[16:19]
	v_pk_mul_f32 v[20:21], v[20:21], v[40:41] op_sel_hi:[1,0]
	v_fmac_f32_e32 v88, v64, v40
	v_mov_b32_e32 v81, v82
	s_waitcnt lgkmcnt(0)
	v_mfma_f32_16x16x32_bf16 v[20:23], v[200:203], v[42:45], v[20:23]
	v_cvt_pk_bf16_f32 v42, v84, v41
	v_cvt_pk_bf16_f32 v43, v83, v85
	v_cvt_pk_bf16_f32 v44, v86, v87
	v_cvt_pk_bf16_f32 v45, v50, v51
	v_mov_b32_e32 v64, v88
	s_waitcnt lgkmcnt(0)
	v_mfma_f32_16x16x32_bf16 v[8:11], v[204:207], v[42:45], v[8:11]
	s_waitcnt lgkmcnt(0)
	v_mfma_f32_16x16x32_bf16 v[12:15], v[208:211], v[42:45], v[12:15]
	s_waitcnt lgkmcnt(0)
	v_mfma_f32_16x16x32_bf16 v[16:19], v[212:215], v[42:45], v[16:19]
	s_waitcnt lgkmcnt(0)
	v_mfma_f32_16x16x32_bf16 v[20:23], v[216:219], v[42:45], v[20:23]

; template <int DQK, int DV, bool CAUSAL, bool MLA> ...
;     ...
;         if (kt + 1 < nkt) ATT_PREFETCH(kt + 1);
;         const int qw0 = q0 + wv * 16;
;         if (CAUSAL && 64 * kt > qw0 + 15) continue;
;         f32x4 sT[4];
; #pragma unroll
;         for (int k4 = 0; k4 < 4; ++k4) { sT[k4] = (f32x4){0.f, 0.f, 0.f, 0.f};
; #pragma unroll
;             for (int ks = 0; ks < NKS; ++ks) { const bf16x8 a = *(const bf16x8*)(Ks + (16 * k4 + j) * KS + (32 * ks + 8 * g) * 2);
;                 sT[k4] = __builtin_amdgcn_mfma_f32_16x16x32_bf16(a, qf[ks], sT[k4], 0, 0, 0); } }
;         if (CAUSAL && 64 * kt + 63 > qw0) {
; #pragma unroll
;             for (int k4 = 0; k4 < 4; ++k4)
; #pragma unroll
;                 for (int r = 0; r < 4; ++r) if (64 * kt + 16 * k4 + 4 * g + r > qrow) sT[k4][r] = -INFINITY;
;         }
;     ...
;             for (int d = 0; d < NDT; ++d) { const unsigned char* vp = Vs + (16 * d + j) * VS + (32 * kc + 4 * g) * 2;
;                 const u32x2 lo = *(const u32x2*)vp, hi = *(const u32x2*)(vp + 32); u32x4 w; w.x = lo.x; w.y = lo.y; w.z = hi.x; w.w = hi.y;
.LBB0_1440:
	s_or_b64 exec, exec, s[4:5]
	s_add_i32 s42, s0, 64
	v_lshl_add_u64 v[36:37], s[42:43], 1, v[58:59]
	global_load_dwordx4 v[36:39], v[36:37], off
	v_cmp_le_i32_e64 s[4:5], s0, v68
	s_and_saveexec_b64 s[14:15], s[4:5]
	s_cbranch_execz .LBB0_1431
	v_add_u32_e32 v86, v67, v69
	ds_read_b128 v[98:101], v86
	ds_read_b128 v[102:105], v86 offset:64
	ds_read_b128 v[106:109], v86 offset:128
	ds_read_b128 v[110:113], v86 offset:3328
	ds_read_b128 v[114:117], v86 offset:3392
	ds_read_b128 v[118:121], v86 offset:3456
	ds_read_b128 v[122:125], v86 offset:6656
	ds_read_b128 v[126:129], v86 offset:6720
	ds_read_b128 v[130:133], v86 offset:6784
	ds_read_b128 v[134:137], v86 offset:9984
	ds_read_b128 v[140:143], v86 offset:10048
	ds_read_b128 v[154:157], v86 offset:10112
	v_add_u32_e32 v158, v65, v66
	v_add_u32_e32 v159, 0x3000, v158
	v_add_u32_e32 v160, 0x3800, v158
	v_add_u32_e32 v161, 0x4000, v158
	v_add_u32_e32 v158, 0x4800, v158
	s_add_i32 s4, s0, 63
	v_cmp_gt_i32_e64 s[4:5], s4, v72
	s_waitcnt lgkmcnt(9)
	v_mfma_f32_16x16x32_bf16 v[44:47], v[98:101], v[32:35], 0
	v_mfma_f32_16x16x32_bf16 v[44:47], v[102:105], v[28:31], v[44:47]
	v_mfma_f32_16x16x32_bf16 v[44:47], v[106:109], v[24:27], v[44:47]
	ds_read2_b64 v[188:191], v159 offset0:128 offset1:132
	ds_read2_b64 v[192:195], v160 offset0:160 offset1:164
	ds_read2_b64 v[196:199], v161 offset0:192 offset1:196
	ds_read2_b64 v[200:203], v158 offset0:224 offset1:228
	s_waitcnt lgkmcnt(10)
	v_mfma_f32_16x16x32_bf16 v[52:55], v[110:113], v[32:35], 0
	v_mfma_f32_16x16x32_bf16 v[52:55], v[114:117], v[28:31], v[52:55]
	v_mfma_f32_16x16x32_bf16 v[52:55], v[118:121], v[24:27], v[52:55]
	ds_read2_b64 v[204:207], v159 offset0:136 offset1:140
	ds_read2_b64 v[208:211], v160 offset0:168 offset1:172
	ds_read2_b64 v[212:215], v161 offset0:200 offset1:204
	ds_read2_b64 v[216:219], v158 offset0:232 offset1:236
	s_waitcnt lgkmcnt(11)
	v_mfma_f32_16x16x32_bf16 v[40:43], v[122:125], v[32:35], 0
	v_mfma_f32_16x16x32_bf16 v[40:43], v[126:129], v[28:31], v[40:43]
	v_mfma_f32_16x16x32_bf16 v[40:43], v[130:133], v[24:27], v[40:43]
	s_waitcnt lgkmcnt(8)
	v_mfma_f32_16x16x32_bf16 v[48:51], v[134:137], v[32:35], 0
	v_mfma_f32_16x16x32_bf16 v[48:51], v[140:143], v[28:31], v[48:51]
	v_mfma_f32_16x16x32_bf16 v[48:51], v[154:157], v[24:27], v[48:51]
	s_and_saveexec_b64 s[16:17], s[4:5]
	s_cbranch_execz .LBB0_1430
	v_add_u32_e32 v82, s0, v57
	v_cmp_gt_i32_e64 s[4:5], v82, v56
	s_nop 1
	v_cndmask_b32_e64 v83, v44, v183, s[4:5]
	v_cmp_lt_i32_e64 s[4:5], v82, v56
	s_nop 1
	v_cndmask_b32_e64 v44, v83, v44, s[4:5]
	v_add_u32_e32 v83, 2, v82
	v_cndmask_b32_e64 v45, v183, v45, s[4:5]
	v_cmp_le_i32_e64 s[4:5], v83, v56
	v_add_u32_e32 v83, 3, v82
	s_nop 0
	v_cndmask_b32_e64 v46, v183, v46, s[4:5]
	v_cmp_le_i32_e64 s[4:5], v83, v56
	v_add_u32_e32 v83, 16, v82
	s_nop 0
	v_cndmask_b32_e64 v47, v183, v47, s[4:5]
	v_cmp_le_i32_e64 s[4:5], v83, v56
	v_add_u32_e32 v83, 17, v82
	s_nop 0
	v_cndmask_b32_e64 v52, v183, v52, s[4:5]
	v_cmp_le_i32_e64 s[4:5], v83, v56
	v_add_u32_e32 v83, 18, v82
	s_nop 0
	v_cndmask_b32_e64 v53, v183, v53, s[4:5]
	v_cmp_le_i32_e64 s[4:5], v83, v56
	v_add_u32_e32 v83, 19, v82
	s_nop 0
	v_cndmask_b32_e64 v54, v183, v54, s[4:5]
	v_cmp_le_i32_e64 s[4:5], v83, v56
	v_add_u32_e32 v83, 32, v82
	s_nop 0
	v_cndmask_b32_e64 v55, v183, v55, s[4:5]
	v_cmp_le_i32_e64 s[4:5], v83, v56
	v_add_u32_e32 v83, 33, v82
	s_nop 0
	v_cndmask_b32_e64 v40, v183, v40, s[4:5]
	v_cmp_le_i32_e64 s[4:5], v83, v56
	v_add_u32_e32 v83, 34, v82
	s_nop 0
	v_cndmask_b32_e64 v41, v183, v41, s[4:5]
	v_cmp_le_i32_e64 s[4:5], v83, v56
	v_add_u32_e32 v83, 35, v82
	s_nop 0
	v_cndmask_b32_e64 v42, v183, v42, s[4:5]
	v_cmp_le_i32_e64 s[4:5], v83, v56
	v_add_u32_e32 v83, 48, v82
	s_nop 0
	v_cndmask_b32_e64 v43, v183, v43, s[4:5]
	v_cmp_le_i32_e64 s[4:5], v83, v56
	v_add_u32_e32 v83, 49, v82
	s_nop 0
	v_cndmask_b32_e64 v48, v183, v48, s[4:5]
	v_cmp_le_i32_e64 s[4:5], v83, v56
	v_add_u32_e32 v83, 50, v82
	v_add_u32_e32 v82, 51, v82
	v_cndmask_b32_e64 v49, v183, v49, s[4:5]
	v_cmp_le_i32_e64 s[4:5], v83, v56
	s_nop 1
	v_cndmask_b32_e64 v50, v183, v50, s[4:5]
	v_cmp_le_i32_e64 s[4:5], v82, v56
	s_nop 1
	v_cndmask_b32_e64 v51, v183, v51, s[4:5]
	s_branch .LBB0_1430

.LBB0_1721:
	v_lshl_or_b32 v138, s42, 8, v158
	v_lshl_add_u32 v140, s50, 8, v156
	v_ashrrev_i32_e32 v139, 31, v138
	v_ashrrev_i32_e32 v141, 31, v140
	v_readlane_b32 s4, v254, 6
	v_lshlrev_b64 v[142:143], 11, v[140:141]
	v_readlane_b32 s5, v254, 7
	s_andn2_b64 vcc, exec, s[8:9]
	s_nop 0
	v_lshl_add_u64 v[142:143], s[4:5], 0, v[142:143]
	v_lshl_add_u64 v[142:143], v[138:139], 1, v[142:143]
	v_mov_b32_e32 v166, v140
	v_ashrrev_i32_e32 v167, 31, v166
	v_lshlrev_b64 v[166:167], 11, v[166:167]
	v_lshl_add_u64 v[166:167], s[4:5], 0, v[166:167]
	v_lshl_add_u64 v[166:167], v[138:139], 1, v[166:167]
	global_load_dwordx4 v[192:195], v[166:167], off
	global_load_dwordx4 v[196:199], v[166:167], off offset:256
	v_add_u32_e32 v166, 16, v140
	v_ashrrev_i32_e32 v167, 31, v166
	v_lshlrev_b64 v[166:167], 11, v[166:167]
	v_lshl_add_u64 v[166:167], s[4:5], 0, v[166:167]
	v_lshl_add_u64 v[166:167], v[138:139], 1, v[166:167]
	global_load_dwordx4 v[200:203], v[166:167], off
	global_load_dwordx4 v[204:207], v[166:167], off offset:256
	v_add_u32_e32 v166, 32, v140
	v_ashrrev_i32_e32 v167, 31, v166
	v_lshlrev_b64 v[166:167], 11, v[166:167]
	v_lshl_add_u64 v[166:167], s[4:5], 0, v[166:167]
	v_lshl_add_u64 v[166:167], v[138:139], 1, v[166:167]
	global_load_dwordx4 v[208:211], v[166:167], off
	global_load_dwordx4 v[212:215], v[166:167], off offset:256
	v_add_u32_e32 v166, 48, v140
	v_ashrrev_i32_e32 v167, 31, v166
	v_lshlrev_b64 v[166:167], 11, v[166:167]
	v_lshl_add_u64 v[166:167], s[4:5], 0, v[166:167]
	v_lshl_add_u64 v[166:167], v[138:139], 1, v[166:167]
	global_load_dwordx4 v[216:219], v[166:167], off
	global_load_dwordx4 v[220:223], v[166:167], off offset:256
	v_add_u32_e32 v166, 128, v140
	v_ashrrev_i32_e32 v167, 31, v166
	v_lshlrev_b64 v[166:167], 11, v[166:167]
	v_lshl_add_u64 v[166:167], s[4:5], 0, v[166:167]
	v_lshl_add_u64 v[166:167], v[138:139], 1, v[166:167]
	global_load_dwordx4 v[224:227], v[166:167], off
	global_load_dwordx4 v[228:231], v[166:167], off offset:256
	v_add_u32_e32 v166, 144, v140
	v_ashrrev_i32_e32 v167, 31, v166
	v_lshlrev_b64 v[166:167], 11, v[166:167]
	v_lshl_add_u64 v[166:167], s[4:5], 0, v[166:167]
	v_lshl_add_u64 v[166:167], v[138:139], 1, v[166:167]
	global_load_dwordx4 v[232:235], v[166:167], off
	global_load_dwordx4 v[236:239], v[166:167], off offset:256
	s_waitcnt vmcnt(0)
	s_waitcnt lgkmcnt(0)
	v_lshlrev_b32_e32 v164, 16, v192
	v_and_b32_e32 v165, 0xffff0000, v192
	v_lshlrev_b32_e32 v160, 16, v193
	v_and_b32_e32 v161, 0xffff0000, v193
	v_pk_add_f32 v[126:127], v[126:127], v[160:161]
	v_lshlrev_b32_e32 v160, 16, v194
	v_and_b32_e32 v161, 0xffff0000, v194
	v_pk_add_f32 v[120:121], v[120:121], v[160:161]
	v_lshlrev_b32_e32 v160, 16, v195
	v_and_b32_e32 v161, 0xffff0000, v195
	v_pk_add_f32 v[122:123], v[122:123], v[160:161]
	v_cndmask_b32_e64 v160, 0, 1, s[8:9]
	v_pk_add_f32 v[124:125], v[124:125], v[164:165]
	v_cmp_ne_u32_e64 s[4:5], 1, v160
	s_cbranch_vccnz .LBB0_1723
	v_cvt_pk_bf16_f32 v160, v124, v125
	v_cvt_pk_bf16_f32 v161, v126, v127
	v_cvt_pk_bf16_f32 v162, v120, v121
	v_cvt_pk_bf16_f32 v163, v122, v123
	global_store_dwordx4 v[142:143], v[160:163], off
.LBB0_1723:
	s_and_b64 vcc, exec, s[4:5]
	s_waitcnt lgkmcnt(0)
	v_lshlrev_b32_e32 v164, 16, v196
	v_and_b32_e32 v165, 0xffff0000, v196
	v_lshlrev_b32_e32 v160, 16, v197
	v_and_b32_e32 v161, 0xffff0000, v197
	v_pk_add_f32 v[118:119], v[118:119], v[160:161]
	v_lshlrev_b32_e32 v160, 16, v198
	v_and_b32_e32 v161, 0xffff0000, v198
	v_pk_add_f32 v[112:113], v[112:113], v[160:161]
	v_lshlrev_b32_e32 v160, 16, v199
	v_and_b32_e32 v161, 0xffff0000, v199
	v_pk_add_f32 v[116:117], v[116:117], v[164:165]
	v_pk_add_f32 v[114:115], v[114:115], v[160:161]
	s_cbranch_vccnz .LBB0_1725
	v_cvt_pk_bf16_f32 v160, v116, v117
	v_cvt_pk_bf16_f32 v161, v118, v119
	v_cvt_pk_bf16_f32 v162, v112, v113
	v_cvt_pk_bf16_f32 v163, v114, v115
	global_store_dwordx4 v[142:143], v[160:163], off offset:256
.LBB0_1725:
	v_pk_mul_f32 v[116:117], v[116:117], v[116:117]
	v_pk_mul_f32 v[118:119], v[118:119], v[118:119]
	v_pk_mul_f32 v[112:113], v[112:113], v[112:113]
	v_add_f32_e32 v118, v118, v119
	v_add_f32_e32 v116, v116, v117
	v_pk_mul_f32 v[114:115], v[114:115], v[114:115]
	v_add_f32_e32 v116, v116, v118
	v_add_f32_e32 v112, v112, v113
	v_pk_mul_f32 v[124:125], v[124:125], v[124:125]
	v_pk_mul_f32 v[126:127], v[126:127], v[126:127]
	v_add_f32_e32 v112, v112, v116
	v_add_f32_e32 v113, v114, v115
	v_pk_mul_f32 v[120:121], v[120:121], v[120:121]
	v_add_f32_e32 v112, v113, v112
	v_add_f32_e32 v113, v126, v127
	v_add_f32_e32 v114, v124, v125
	v_pk_mul_f32 v[122:123], v[122:123], v[122:123]
	v_add_f32_e32 v113, v114, v113
	v_add_f32_e32 v114, v120, v121
	v_add_f32_e32 v113, v114, v113
	v_add_f32_e32 v114, v122, v123
	v_add_f32_e32 v113, v114, v113
	v_add_f32_e32 v112, v113, v112
	ds_bpermute_b32 v113, v154, v112
	s_lshl_b32 s34, s42, 2
	s_ashr_i32 s35, s34, 31
	s_waitcnt lgkmcnt(0)
	v_add_f32_e32 v112, v112, v113
	ds_bpermute_b32 v113, v155, v112
	s_and_saveexec_b64 s[44:45], s[26:27]
	s_cbranch_execz .LBB0_1727
	v_readlane_b32 s50, v254, 8
	v_lshlrev_b64 v[114:115], 6, v[140:141]
	v_readlane_b32 s51, v254, 9
	s_lshl_b32 s42, s92, 2
	s_waitcnt lgkmcnt(0)
	v_add_f32_e32 v112, v112, v113
	v_lshl_add_u64 v[114:115], s[50:51], 0, v[114:115]
	v_lshl_add_u64 v[114:115], s[34:35], 2, v[114:115]
	v_lshl_add_u64 v[114:115], v[114:115], 0, s[42:43]
	global_store_dword v[114:115], v112, off
.LBB0_1727:
	s_or_b64 exec, exec, s[44:45]
	v_or_b32_e32 v112, 16, v140
	s_waitcnt lgkmcnt(0)
	v_ashrrev_i32_e32 v113, 31, v112
	v_readlane_b32 s44, v254, 6
	v_lshlrev_b64 v[114:115], 11, v[112:113]
	v_readlane_b32 s45, v254, 7
	s_and_b64 vcc, exec, s[4:5]
	s_nop 0
	v_lshl_add_u64 v[114:115], s[44:45], 0, v[114:115]
	v_lshl_add_u64 v[114:115], v[138:139], 1, v[114:115]
	s_waitcnt lgkmcnt(0)
	v_lshlrev_b32_e32 v120, 16, v200
	v_and_b32_e32 v121, 0xffff0000, v200
	v_lshlrev_b32_e32 v116, 16, v201
	v_and_b32_e32 v117, 0xffff0000, v201
	v_pk_add_f32 v[110:111], v[110:111], v[116:117]
	v_lshlrev_b32_e32 v116, 16, v202
	v_and_b32_e32 v117, 0xffff0000, v202
	v_pk_add_f32 v[104:105], v[104:105], v[116:117]
	v_lshlrev_b32_e32 v116, 16, v203
	v_and_b32_e32 v117, 0xffff0000, v203
	v_pk_add_f32 v[108:109], v[108:109], v[120:121]
	v_pk_add_f32 v[106:107], v[106:107], v[116:117]
	s_cbranch_vccnz .LBB0_1729
	v_cvt_pk_bf16_f32 v116, v108, v109
	v_cvt_pk_bf16_f32 v117, v110, v111
	v_cvt_pk_bf16_f32 v118, v104, v105
	v_cvt_pk_bf16_f32 v119, v106, v107
	global_store_dwordx4 v[114:115], v[116:119], off
.LBB0_1729:
	s_and_b64 vcc, exec, s[4:5]
	s_waitcnt lgkmcnt(0)
	v_lshlrev_b32_e32 v120, 16, v204
	v_and_b32_e32 v121, 0xffff0000, v204
	v_lshlrev_b32_e32 v116, 16, v205
	v_and_b32_e32 v117, 0xffff0000, v205
	v_pk_add_f32 v[102:103], v[102:103], v[116:117]
	v_lshlrev_b32_e32 v116, 16, v206
	v_and_b32_e32 v117, 0xffff0000, v206
	v_pk_add_f32 v[96:97], v[96:97], v[116:117]
	v_lshlrev_b32_e32 v116, 16, v207
	v_and_b32_e32 v117, 0xffff0000, v207
	v_pk_add_f32 v[100:101], v[100:101], v[120:121]
	v_pk_add_f32 v[98:99], v[98:99], v[116:117]
	s_cbranch_vccnz .LBB0_1731
	v_cvt_pk_bf16_f32 v116, v100, v101
	v_cvt_pk_bf16_f32 v117, v102, v103
	v_cvt_pk_bf16_f32 v118, v96, v97
	v_cvt_pk_bf16_f32 v119, v98, v99
	global_store_dwordx4 v[114:115], v[116:119], off offset:256
.LBB0_1731:
	v_pk_mul_f32 v[100:101], v[100:101], v[100:101]
	v_pk_mul_f32 v[102:103], v[102:103], v[102:103]
	v_pk_mul_f32 v[96:97], v[96:97], v[96:97]
	v_add_f32_e32 v102, v102, v103
	v_add_f32_e32 v100, v100, v101
	v_pk_mul_f32 v[98:99], v[98:99], v[98:99]
	v_add_f32_e32 v100, v100, v102
	v_add_f32_e32 v96, v96, v97
	v_pk_mul_f32 v[108:109], v[108:109], v[108:109]
	v_pk_mul_f32 v[110:111], v[110:111], v[110:111]
	v_add_f32_e32 v96, v96, v100
	v_add_f32_e32 v97, v98, v99
	v_pk_mul_f32 v[104:105], v[104:105], v[104:105]
	v_add_f32_e32 v96, v97, v96
	v_add_f32_e32 v97, v110, v111
	v_add_f32_e32 v98, v108, v109
	v_pk_mul_f32 v[106:107], v[106:107], v[106:107]
	v_add_f32_e32 v97, v98, v97
	v_add_f32_e32 v98, v104, v105
	v_add_f32_e32 v97, v98, v97
	v_add_f32_e32 v98, v106, v107
	v_add_f32_e32 v97, v98, v97
	v_add_f32_e32 v96, v97, v96
	ds_bpermute_b32 v97, v154, v96
	s_waitcnt lgkmcnt(0)
	v_add_f32_e32 v96, v96, v97
	ds_bpermute_b32 v97, v155, v96
	s_and_saveexec_b64 s[44:45], s[26:27]
	s_cbranch_execz .LBB0_1733
	v_readlane_b32 s50, v254, 8
	v_lshlrev_b64 v[98:99], 6, v[112:113]
	v_readlane_b32 s51, v254, 9
	s_lshl_b32 s42, s92, 2
	s_waitcnt lgkmcnt(0)
	v_add_f32_e32 v96, v96, v97
	v_lshl_add_u64 v[98:99], s[50:51], 0, v[98:99]
	v_lshl_add_u64 v[98:99], s[34:35], 2, v[98:99]
	v_lshl_add_u64 v[98:99], v[98:99], 0, s[42:43]
	global_store_dword v[98:99], v96, off
.LBB0_1733:
	s_or_b64 exec, exec, s[44:45]
	v_or_b32_e32 v96, 32, v140
	s_waitcnt lgkmcnt(0)
	v_ashrrev_i32_e32 v97, 31, v96
	v_readlane_b32 s44, v254, 6
	v_lshlrev_b64 v[98:99], 11, v[96:97]
	v_readlane_b32 s45, v254, 7
	s_and_b64 vcc, exec, s[4:5]
	s_nop 0
	v_lshl_add_u64 v[98:99], s[44:45], 0, v[98:99]
	v_lshl_add_u64 v[98:99], v[138:139], 1, v[98:99]
	s_waitcnt lgkmcnt(0)
	v_lshlrev_b32_e32 v104, 16, v208
	v_and_b32_e32 v105, 0xffff0000, v208
	v_lshlrev_b32_e32 v100, 16, v209
	v_and_b32_e32 v101, 0xffff0000, v209
	v_pk_add_f32 v[94:95], v[94:95], v[100:101]
	v_lshlrev_b32_e32 v100, 16, v210
	v_and_b32_e32 v101, 0xffff0000, v210
	v_pk_add_f32 v[88:89], v[88:89], v[100:101]
	v_lshlrev_b32_e32 v100, 16, v211
	v_and_b32_e32 v101, 0xffff0000, v211
	v_pk_add_f32 v[92:93], v[92:93], v[104:105]
	v_pk_add_f32 v[90:91], v[90:91], v[100:101]
	s_cbranch_vccnz .LBB0_1735
	v_cvt_pk_bf16_f32 v100, v92, v93
	v_cvt_pk_bf16_f32 v101, v94, v95
	v_cvt_pk_bf16_f32 v102, v88, v89
	v_cvt_pk_bf16_f32 v103, v90, v91
	global_store_dwordx4 v[98:99], v[100:103], off
.LBB0_1735:
	s_and_b64 vcc, exec, s[4:5]
	s_waitcnt lgkmcnt(0)
	v_lshlrev_b32_e32 v104, 16, v212
	v_and_b32_e32 v105, 0xffff0000, v212
	v_lshlrev_b32_e32 v100, 16, v213
	v_and_b32_e32 v101, 0xffff0000, v213
	v_pk_add_f32 v[86:87], v[86:87], v[100:101]
	v_lshlrev_b32_e32 v100, 16, v214
	v_and_b32_e32 v101, 0xffff0000, v214
	v_pk_add_f32 v[80:81], v[80:81], v[100:101]
	v_lshlrev_b32_e32 v100, 16, v215
	v_and_b32_e32 v101, 0xffff0000, v215
	v_pk_add_f32 v[84:85], v[84:85], v[104:105]
	v_pk_add_f32 v[82:83], v[82:83], v[100:101]
	s_cbranch_vccnz .LBB0_1737
	v_cvt_pk_bf16_f32 v100, v84, v85
	v_cvt_pk_bf16_f32 v101, v86, v87
	v_cvt_pk_bf16_f32 v102, v80, v81
	v_cvt_pk_bf16_f32 v103, v82, v83
	global_store_dwordx4 v[98:99], v[100:103], off offset:256
.LBB0_1737:
	v_pk_mul_f32 v[84:85], v[84:85], v[84:85]
	v_pk_mul_f32 v[86:87], v[86:87], v[86:87]
	v_pk_mul_f32 v[80:81], v[80:81], v[80:81]
	v_add_f32_e32 v86, v86, v87
	v_add_f32_e32 v84, v84, v85
	v_pk_mul_f32 v[82:83], v[82:83], v[82:83]
	v_add_f32_e32 v84, v84, v86
	v_add_f32_e32 v80, v80, v81
	v_pk_mul_f32 v[92:93], v[92:93], v[92:93]
	v_pk_mul_f32 v[94:95], v[94:95], v[94:95]
	v_add_f32_e32 v80, v80, v84
	v_add_f32_e32 v81, v82, v83
	v_pk_mul_f32 v[88:89], v[88:89], v[88:89]
	v_add_f32_e32 v80, v81, v80
	v_add_f32_e32 v81, v94, v95
	v_add_f32_e32 v82, v92, v93
	v_pk_mul_f32 v[90:91], v[90:91], v[90:91]
	v_add_f32_e32 v81, v82, v81
	v_add_f32_e32 v82, v88, v89
	v_add_f32_e32 v81, v82, v81
	v_add_f32_e32 v82, v90, v91
	v_add_f32_e32 v81, v82, v81
	v_add_f32_e32 v80, v81, v80
	ds_bpermute_b32 v81, v154, v80
	s_waitcnt lgkmcnt(0)
	v_add_f32_e32 v80, v80, v81
	ds_bpermute_b32 v81, v155, v80
	s_and_saveexec_b64 s[44:45], s[26:27]
	s_cbranch_execz .LBB0_1739
	v_readlane_b32 s50, v254, 8
	v_lshlrev_b64 v[82:83], 6, v[96:97]
	v_readlane_b32 s51, v254, 9
	s_lshl_b32 s42, s92, 2
	s_waitcnt lgkmcnt(0)
	v_add_f32_e32 v80, v80, v81
	v_lshl_add_u64 v[82:83], s[50:51], 0, v[82:83]
	v_lshl_add_u64 v[82:83], s[34:35], 2, v[82:83]
	v_lshl_add_u64 v[82:83], v[82:83], 0, s[42:43]
	global_store_dword v[82:83], v80, off
.LBB0_1739:
	s_or_b64 exec, exec, s[44:45]
	v_or_b32_e32 v80, 48, v140
	s_waitcnt lgkmcnt(0)
	v_ashrrev_i32_e32 v81, 31, v80
	v_readlane_b32 s44, v254, 6
	v_lshlrev_b64 v[82:83], 11, v[80:81]
	v_readlane_b32 s45, v254, 7
	s_and_b64 vcc, exec, s[4:5]
	s_nop 0
	v_lshl_add_u64 v[82:83], s[44:45], 0, v[82:83]
	v_lshl_add_u64 v[82:83], v[138:139], 1, v[82:83]
	s_waitcnt lgkmcnt(0)
	v_lshlrev_b32_e32 v88, 16, v216
	v_and_b32_e32 v89, 0xffff0000, v216
	v_lshlrev_b32_e32 v84, 16, v217
	v_and_b32_e32 v85, 0xffff0000, v217
	v_pk_add_f32 v[78:79], v[78:79], v[84:85]
	v_lshlrev_b32_e32 v84, 16, v218
	v_and_b32_e32 v85, 0xffff0000, v218
	v_pk_add_f32 v[72:73], v[72:73], v[84:85]
	v_lshlrev_b32_e32 v84, 16, v219
	v_and_b32_e32 v85, 0xffff0000, v219
	v_pk_add_f32 v[76:77], v[76:77], v[88:89]
	v_pk_add_f32 v[74:75], v[74:75], v[84:85]
	s_cbranch_vccnz .LBB0_1741
	v_cvt_pk_bf16_f32 v84, v76, v77
	v_cvt_pk_bf16_f32 v85, v78, v79
	v_cvt_pk_bf16_f32 v86, v72, v73
	v_cvt_pk_bf16_f32 v87, v74, v75
	global_store_dwordx4 v[82:83], v[84:87], off
.LBB0_1741:
	s_and_b64 vcc, exec, s[4:5]
	s_waitcnt lgkmcnt(0)
	v_lshlrev_b32_e32 v88, 16, v220
	v_and_b32_e32 v89, 0xffff0000, v220
	v_lshlrev_b32_e32 v84, 16, v221
	v_and_b32_e32 v85, 0xffff0000, v221
	v_pk_add_f32 v[70:71], v[70:71], v[84:85]
	v_lshlrev_b32_e32 v84, 16, v222
	v_and_b32_e32 v85, 0xffff0000, v222
	v_pk_add_f32 v[64:65], v[64:65], v[84:85]
	v_lshlrev_b32_e32 v84, 16, v223
	v_and_b32_e32 v85, 0xffff0000, v223
	v_pk_add_f32 v[68:69], v[68:69], v[88:89]
	v_pk_add_f32 v[66:67], v[66:67], v[84:85]
	s_cbranch_vccnz .LBB0_1743
	v_cvt_pk_bf16_f32 v84, v68, v69
	v_cvt_pk_bf16_f32 v85, v70, v71
	v_cvt_pk_bf16_f32 v86, v64, v65
	v_cvt_pk_bf16_f32 v87, v66, v67
	global_store_dwordx4 v[82:83], v[84:87], off offset:256
.LBB0_1743:
	v_pk_mul_f32 v[68:69], v[68:69], v[68:69]
	v_pk_mul_f32 v[70:71], v[70:71], v[70:71]
	v_pk_mul_f32 v[64:65], v[64:65], v[64:65]
	v_add_f32_e32 v70, v70, v71
	v_add_f32_e32 v68, v68, v69
	v_pk_mul_f32 v[66:67], v[66:67], v[66:67]
	v_add_f32_e32 v68, v68, v70
	v_add_f32_e32 v64, v64, v65
	v_pk_mul_f32 v[76:77], v[76:77], v[76:77]
	v_pk_mul_f32 v[78:79], v[78:79], v[78:79]
	v_add_f32_e32 v64, v64, v68
	v_add_f32_e32 v65, v66, v67
	v_pk_mul_f32 v[72:73], v[72:73], v[72:73]
	v_add_f32_e32 v64, v65, v64
	v_add_f32_e32 v65, v78, v79
	v_add_f32_e32 v66, v76, v77
	v_pk_mul_f32 v[74:75], v[74:75], v[74:75]
	v_add_f32_e32 v65, v66, v65
	v_add_f32_e32 v66, v72, v73
	v_add_f32_e32 v65, v66, v65
	v_add_f32_e32 v66, v74, v75
	v_add_f32_e32 v65, v66, v65
	v_add_f32_e32 v64, v65, v64
	ds_bpermute_b32 v65, v154, v64
	s_waitcnt lgkmcnt(0)
	v_add_f32_e32 v64, v64, v65
	ds_bpermute_b32 v65, v155, v64
	s_and_saveexec_b64 s[44:45], s[26:27]
	s_cbranch_execz .LBB0_1745
	v_readlane_b32 s50, v254, 8
	v_lshlrev_b64 v[66:67], 6, v[80:81]
	v_readlane_b32 s51, v254, 9
	s_lshl_b32 s42, s92, 2
	s_waitcnt lgkmcnt(0)
	v_add_f32_e32 v64, v64, v65
	v_lshl_add_u64 v[66:67], s[50:51], 0, v[66:67]
	v_lshl_add_u64 v[66:67], s[34:35], 2, v[66:67]
	v_lshl_add_u64 v[66:67], v[66:67], 0, s[42:43]
	global_store_dword v[66:67], v64, off
.LBB0_1745:
	s_or_b64 exec, exec, s[44:45]
	v_add_u32_e32 v64, 0x80, v140
	s_waitcnt lgkmcnt(0)
	v_ashrrev_i32_e32 v65, 31, v64
	v_readlane_b32 s44, v254, 6
	v_lshlrev_b64 v[66:67], 11, v[64:65]
	v_readlane_b32 s45, v254, 7
	s_and_b64 vcc, exec, s[4:5]
	s_nop 0
	v_lshl_add_u64 v[66:67], s[44:45], 0, v[66:67]
	v_lshl_add_u64 v[66:67], v[138:139], 1, v[66:67]
	v_add_u32_e32 v166, 160, v140
	v_ashrrev_i32_e32 v167, 31, v166
	v_lshlrev_b64 v[166:167], 11, v[166:167]
	v_lshl_add_u64 v[166:167], s[44:45], 0, v[166:167]
	v_lshl_add_u64 v[166:167], v[138:139], 1, v[166:167]
	global_load_dwordx4 v[192:195], v[166:167], off
	global_load_dwordx4 v[196:199], v[166:167], off offset:256
	v_add_u32_e32 v166, 176, v140
	v_ashrrev_i32_e32 v167, 31, v166
	v_lshlrev_b64 v[166:167], 11, v[166:167]
	v_lshl_add_u64 v[166:167], s[44:45], 0, v[166:167]
	v_lshl_add_u64 v[166:167], v[138:139], 1, v[166:167]
	global_load_dwordx4 v[200:203], v[166:167], off
	global_load_dwordx4 v[204:207], v[166:167], off offset:256
	s_waitcnt lgkmcnt(0)
	v_lshlrev_b32_e32 v72, 16, v224
	v_and_b32_e32 v73, 0xffff0000, v224
	v_lshlrev_b32_e32 v68, 16, v225
	v_and_b32_e32 v69, 0xffff0000, v225
	v_pk_add_f32 v[62:63], v[62:63], v[68:69]
	v_lshlrev_b32_e32 v68, 16, v226
	v_and_b32_e32 v69, 0xffff0000, v226
	v_pk_add_f32 v[56:57], v[56:57], v[68:69]
	v_lshlrev_b32_e32 v68, 16, v227
	v_and_b32_e32 v69, 0xffff0000, v227
	v_pk_add_f32 v[60:61], v[60:61], v[72:73]
	v_pk_add_f32 v[58:59], v[58:59], v[68:69]
	s_cbranch_vccnz .LBB0_1747
	v_cvt_pk_bf16_f32 v68, v60, v61
	v_cvt_pk_bf16_f32 v69, v62, v63
	v_cvt_pk_bf16_f32 v70, v56, v57
	v_cvt_pk_bf16_f32 v71, v58, v59
	global_store_dwordx4 v[66:67], v[68:71], off
.LBB0_1747:
	s_and_b64 vcc, exec, s[4:5]
	s_waitcnt lgkmcnt(0)
	v_lshlrev_b32_e32 v72, 16, v228
	v_and_b32_e32 v73, 0xffff0000, v228
	v_lshlrev_b32_e32 v68, 16, v229
	v_and_b32_e32 v69, 0xffff0000, v229
	v_pk_add_f32 v[54:55], v[54:55], v[68:69]
	v_lshlrev_b32_e32 v68, 16, v230
	v_and_b32_e32 v69, 0xffff0000, v230
	v_pk_add_f32 v[48:49], v[48:49], v[68:69]
	v_lshlrev_b32_e32 v68, 16, v231
	v_and_b32_e32 v69, 0xffff0000, v231
	v_pk_add_f32 v[52:53], v[52:53], v[72:73]
	v_pk_add_f32 v[50:51], v[50:51], v[68:69]
	s_cbranch_vccnz .LBB0_1749
	v_cvt_pk_bf16_f32 v68, v52, v53
	v_cvt_pk_bf16_f32 v69, v54, v55
	v_cvt_pk_bf16_f32 v70, v48, v49
	v_cvt_pk_bf16_f32 v71, v50, v51
	global_store_dwordx4 v[66:67], v[68:71], off offset:256
.LBB0_1749:
	v_pk_mul_f32 v[52:53], v[52:53], v[52:53]
	v_pk_mul_f32 v[54:55], v[54:55], v[54:55]
	v_pk_mul_f32 v[48:49], v[48:49], v[48:49]
	v_add_f32_e32 v54, v54, v55
	v_add_f32_e32 v52, v52, v53
	v_pk_mul_f32 v[50:51], v[50:51], v[50:51]
	v_add_f32_e32 v52, v52, v54
	v_add_f32_e32 v48, v48, v49
	v_pk_mul_f32 v[60:61], v[60:61], v[60:61]
	v_pk_mul_f32 v[62:63], v[62:63], v[62:63]
	v_add_f32_e32 v48, v48, v52
	v_add_f32_e32 v49, v50, v51
	v_pk_mul_f32 v[56:57], v[56:57], v[56:57]
	v_add_f32_e32 v48, v49, v48
	v_add_f32_e32 v49, v62, v63
	v_add_f32_e32 v50, v60, v61
	v_pk_mul_f32 v[58:59], v[58:59], v[58:59]
	v_add_f32_e32 v49, v50, v49
	v_add_f32_e32 v50, v56, v57
	v_add_f32_e32 v49, v50, v49
	v_add_f32_e32 v50, v58, v59
	v_add_f32_e32 v49, v50, v49
	v_add_f32_e32 v48, v49, v48
	ds_bpermute_b32 v49, v154, v48
	s_waitcnt lgkmcnt(0)
	v_add_f32_e32 v48, v48, v49
	ds_bpermute_b32 v49, v155, v48
	s_and_saveexec_b64 s[44:45], s[26:27]
	s_cbranch_execz .LBB0_1751
	v_readlane_b32 s50, v254, 8
	v_lshlrev_b64 v[50:51], 6, v[64:65]
	v_readlane_b32 s51, v254, 9
	s_lshl_b32 s42, s92, 2
	s_waitcnt lgkmcnt(0)
	v_add_f32_e32 v48, v48, v49
	v_lshl_add_u64 v[50:51], s[50:51], 0, v[50:51]
	v_lshl_add_u64 v[50:51], s[34:35], 2, v[50:51]
	v_lshl_add_u64 v[50:51], v[50:51], 0, s[42:43]
	global_store_dword v[50:51], v48, off
.LBB0_1751:
	s_or_b64 exec, exec, s[44:45]
	v_add_u32_e32 v48, 0x90, v140
	s_waitcnt lgkmcnt(0)
	v_ashrrev_i32_e32 v49, 31, v48
	v_readlane_b32 s44, v254, 6
	v_lshlrev_b64 v[50:51], 11, v[48:49]
	v_readlane_b32 s45, v254, 7
	s_and_b64 vcc, exec, s[4:5]
	s_nop 0
	v_lshl_add_u64 v[50:51], s[44:45], 0, v[50:51]
	v_lshl_add_u64 v[50:51], v[138:139], 1, v[50:51]
	s_waitcnt lgkmcnt(0)
	v_lshlrev_b32_e32 v56, 16, v232
	v_and_b32_e32 v57, 0xffff0000, v232
	v_lshlrev_b32_e32 v52, 16, v233
	v_and_b32_e32 v53, 0xffff0000, v233
	v_pk_add_f32 v[46:47], v[46:47], v[52:53]
	v_lshlrev_b32_e32 v52, 16, v234
	v_and_b32_e32 v53, 0xffff0000, v234
	v_pk_add_f32 v[40:41], v[40:41], v[52:53]
	v_lshlrev_b32_e32 v52, 16, v235
	v_and_b32_e32 v53, 0xffff0000, v235
	v_pk_add_f32 v[44:45], v[44:45], v[56:57]
	v_pk_add_f32 v[42:43], v[42:43], v[52:53]
	s_cbranch_vccnz .LBB0_1753
	v_cvt_pk_bf16_f32 v52, v44, v45
	v_cvt_pk_bf16_f32 v53, v46, v47
	v_cvt_pk_bf16_f32 v54, v40, v41
	v_cvt_pk_bf16_f32 v55, v42, v43
	global_store_dwordx4 v[50:51], v[52:55], off
.LBB0_1753:
	s_and_b64 vcc, exec, s[4:5]
	s_waitcnt lgkmcnt(0)
	v_lshlrev_b32_e32 v56, 16, v236
	v_and_b32_e32 v57, 0xffff0000, v236
	v_lshlrev_b32_e32 v52, 16, v237
	v_and_b32_e32 v53, 0xffff0000, v237
	v_pk_add_f32 v[38:39], v[38:39], v[52:53]
	v_lshlrev_b32_e32 v52, 16, v238
	v_and_b32_e32 v53, 0xffff0000, v238
	v_pk_add_f32 v[32:33], v[32:33], v[52:53]
	v_lshlrev_b32_e32 v52, 16, v239
	v_and_b32_e32 v53, 0xffff0000, v239
	v_pk_add_f32 v[36:37], v[36:37], v[56:57]
	v_pk_add_f32 v[34:35], v[34:35], v[52:53]
	s_cbranch_vccnz .LBB0_1755
	v_cvt_pk_bf16_f32 v52, v36, v37
	v_cvt_pk_bf16_f32 v53, v38, v39
	v_cvt_pk_bf16_f32 v54, v32, v33
	v_cvt_pk_bf16_f32 v55, v34, v35
	global_store_dwordx4 v[50:51], v[52:55], off offset:256
.LBB0_1755:
	v_pk_mul_f32 v[36:37], v[36:37], v[36:37]
	v_pk_mul_f32 v[38:39], v[38:39], v[38:39]
	v_pk_mul_f32 v[32:33], v[32:33], v[32:33]
	v_add_f32_e32 v38, v38, v39
	v_add_f32_e32 v36, v36, v37
	v_pk_mul_f32 v[34:35], v[34:35], v[34:35]
	v_add_f32_e32 v36, v36, v38
	v_add_f32_e32 v32, v32, v33
	v_pk_mul_f32 v[44:45], v[44:45], v[44:45]
	v_pk_mul_f32 v[46:47], v[46:47], v[46:47]
	v_add_f32_e32 v32, v32, v36
	v_add_f32_e32 v33, v34, v35
	v_pk_mul_f32 v[40:41], v[40:41], v[40:41]
	v_add_f32_e32 v32, v33, v32
	v_add_f32_e32 v33, v46, v47
	v_add_f32_e32 v34, v44, v45
	v_pk_mul_f32 v[42:43], v[42:43], v[42:43]
	v_add_f32_e32 v33, v34, v33
	v_add_f32_e32 v34, v40, v41
	v_add_f32_e32 v33, v34, v33
	v_add_f32_e32 v34, v42, v43
	v_add_f32_e32 v33, v34, v33
	v_add_f32_e32 v32, v33, v32
	ds_bpermute_b32 v33, v154, v32
	s_waitcnt lgkmcnt(0)
	v_add_f32_e32 v32, v32, v33
	ds_bpermute_b32 v33, v155, v32
	s_and_saveexec_b64 s[44:45], s[26:27]
	s_cbranch_execz .LBB0_1757
	v_readlane_b32 s50, v254, 8
	v_lshlrev_b64 v[34:35], 6, v[48:49]
	v_readlane_b32 s51, v254, 9
	s_lshl_b32 s42, s92, 2
	s_waitcnt lgkmcnt(0)
	v_add_f32_e32 v32, v32, v33
	v_lshl_add_u64 v[34:35], s[50:51], 0, v[34:35]
	v_lshl_add_u64 v[34:35], s[34:35], 2, v[34:35]
	v_lshl_add_u64 v[34:35], v[34:35], 0, s[42:43]
	global_store_dword v[34:35], v32, off
.LBB0_1757:
	s_or_b64 exec, exec, s[44:45]
	v_add_u32_e32 v32, 0xa0, v140
	s_waitcnt lgkmcnt(0)
	v_ashrrev_i32_e32 v33, 31, v32
	v_readlane_b32 s44, v254, 6
	v_lshlrev_b64 v[34:35], 11, v[32:33]
	v_readlane_b32 s45, v254, 7
	s_and_b64 vcc, exec, s[4:5]
	s_nop 0
	v_lshl_add_u64 v[34:35], s[44:45], 0, v[34:35]
	v_lshl_add_u64 v[34:35], v[138:139], 1, v[34:35]
	s_waitcnt vmcnt(0)
	s_waitcnt lgkmcnt(0)
	v_lshlrev_b32_e32 v40, 16, v192
	v_and_b32_e32 v41, 0xffff0000, v192
	v_lshlrev_b32_e32 v36, 16, v193
	v_and_b32_e32 v37, 0xffff0000, v193
	v_pk_add_f32 v[30:31], v[30:31], v[36:37]
	v_lshlrev_b32_e32 v36, 16, v194
	v_and_b32_e32 v37, 0xffff0000, v194
	v_pk_add_f32 v[24:25], v[24:25], v[36:37]
	v_lshlrev_b32_e32 v36, 16, v195
	v_and_b32_e32 v37, 0xffff0000, v195
	v_pk_add_f32 v[28:29], v[28:29], v[40:41]
	v_pk_add_f32 v[26:27], v[26:27], v[36:37]
	s_cbranch_vccnz .LBB0_1759
	v_cvt_pk_bf16_f32 v36, v28, v29
	v_cvt_pk_bf16_f32 v37, v30, v31
	v_cvt_pk_bf16_f32 v38, v24, v25
	v_cvt_pk_bf16_f32 v39, v26, v27
	global_store_dwordx4 v[34:35], v[36:39], off
.LBB0_1759:
	s_and_b64 vcc, exec, s[4:5]
	s_waitcnt lgkmcnt(0)
	v_lshlrev_b32_e32 v40, 16, v196
	v_and_b32_e32 v41, 0xffff0000, v196
	v_lshlrev_b32_e32 v36, 16, v197
	v_and_b32_e32 v37, 0xffff0000, v197
	v_pk_add_f32 v[22:23], v[22:23], v[36:37]
	v_lshlrev_b32_e32 v36, 16, v198
	v_and_b32_e32 v37, 0xffff0000, v198
	v_pk_add_f32 v[16:17], v[16:17], v[36:37]
	v_lshlrev_b32_e32 v36, 16, v199
	v_and_b32_e32 v37, 0xffff0000, v199
	v_pk_add_f32 v[20:21], v[20:21], v[40:41]
	v_pk_add_f32 v[18:19], v[18:19], v[36:37]
	s_cbranch_vccnz .LBB0_1761
	v_cvt_pk_bf16_f32 v36, v20, v21
	v_cvt_pk_bf16_f32 v37, v22, v23
	v_cvt_pk_bf16_f32 v38, v16, v17
	v_cvt_pk_bf16_f32 v39, v18, v19
	global_store_dwordx4 v[34:35], v[36:39], off offset:256
.LBB0_1761:
	v_pk_mul_f32 v[20:21], v[20:21], v[20:21]
	v_pk_mul_f32 v[22:23], v[22:23], v[22:23]
	v_pk_mul_f32 v[16:17], v[16:17], v[16:17]
	v_add_f32_e32 v22, v22, v23
	v_add_f32_e32 v20, v20, v21
	v_pk_mul_f32 v[18:19], v[18:19], v[18:19]
	v_add_f32_e32 v20, v20, v22
	v_add_f32_e32 v16, v16, v17
	v_pk_mul_f32 v[28:29], v[28:29], v[28:29]
	v_pk_mul_f32 v[30:31], v[30:31], v[30:31]
	v_add_f32_e32 v16, v16, v20
	v_add_f32_e32 v17, v18, v19
	v_pk_mul_f32 v[24:25], v[24:25], v[24:25]
	v_add_f32_e32 v16, v17, v16
	v_add_f32_e32 v17, v30, v31
	v_add_f32_e32 v18, v28, v29
	v_pk_mul_f32 v[26:27], v[26:27], v[26:27]
	v_add_f32_e32 v17, v18, v17
	v_add_f32_e32 v18, v24, v25
	v_add_f32_e32 v17, v18, v17
	v_add_f32_e32 v18, v26, v27
	v_add_f32_e32 v17, v18, v17
	v_add_f32_e32 v16, v17, v16
	ds_bpermute_b32 v17, v154, v16
	s_waitcnt lgkmcnt(0)
	v_add_f32_e32 v16, v16, v17
	ds_bpermute_b32 v17, v155, v16
	s_and_saveexec_b64 s[44:45], s[26:27]
	s_cbranch_execz .LBB0_1763
	v_readlane_b32 s50, v254, 8
	v_lshlrev_b64 v[18:19], 6, v[32:33]
	v_readlane_b32 s51, v254, 9
	s_lshl_b32 s42, s92, 2
	s_waitcnt lgkmcnt(0)
	v_add_f32_e32 v16, v16, v17
	v_lshl_add_u64 v[18:19], s[50:51], 0, v[18:19]
	v_lshl_add_u64 v[18:19], s[34:35], 2, v[18:19]
	v_lshl_add_u64 v[18:19], v[18:19], 0, s[42:43]
	global_store_dword v[18:19], v16, off
.LBB0_1763:
	s_or_b64 exec, exec, s[44:45]
	v_add_u32_e32 v16, 0xb0, v140
	s_waitcnt lgkmcnt(0)
	v_ashrrev_i32_e32 v17, 31, v16
	v_readlane_b32 s44, v254, 6
	v_lshlrev_b64 v[18:19], 11, v[16:17]
	v_readlane_b32 s45, v254, 7
	s_and_b64 vcc, exec, s[4:5]
	s_nop 0
	v_lshl_add_u64 v[18:19], s[44:45], 0, v[18:19]
	v_lshl_add_u64 v[18:19], v[138:139], 1, v[18:19]
	s_waitcnt lgkmcnt(0)
	v_lshlrev_b32_e32 v24, 16, v200
	v_and_b32_e32 v25, 0xffff0000, v200
	v_lshlrev_b32_e32 v20, 16, v201
	v_and_b32_e32 v21, 0xffff0000, v201
	v_pk_add_f32 v[14:15], v[14:15], v[20:21]
	v_lshlrev_b32_e32 v20, 16, v202
	v_and_b32_e32 v21, 0xffff0000, v202
	v_pk_add_f32 v[8:9], v[8:9], v[20:21]
	v_lshlrev_b32_e32 v20, 16, v203
	v_and_b32_e32 v21, 0xffff0000, v203
	v_pk_add_f32 v[12:13], v[12:13], v[24:25]
	v_pk_add_f32 v[10:11], v[10:11], v[20:21]
	s_cbranch_vccnz .LBB0_1765
	v_cvt_pk_bf16_f32 v20, v12, v13
	v_cvt_pk_bf16_f32 v21, v14, v15
	v_cvt_pk_bf16_f32 v22, v8, v9
	v_cvt_pk_bf16_f32 v23, v10, v11
	global_store_dwordx4 v[18:19], v[20:23], off
.LBB0_1765:
	s_and_b64 vcc, exec, s[4:5]
	s_movk_i32 s51, 0x200
	s_waitcnt lgkmcnt(0)
	v_lshlrev_b32_e32 v24, 16, v204
	v_and_b32_e32 v25, 0xffff0000, v204
	v_lshlrev_b32_e32 v20, 16, v205
	v_and_b32_e32 v21, 0xffff0000, v205
	v_pk_add_f32 v[6:7], v[6:7], v[20:21]
	v_lshlrev_b32_e32 v20, 16, v206
	v_and_b32_e32 v21, 0xffff0000, v206
	v_pk_add_f32 v[0:1], v[0:1], v[20:21]
	v_lshlrev_b32_e32 v20, 16, v207
	v_and_b32_e32 v21, 0xffff0000, v207
	v_pk_add_f32 v[4:5], v[4:5], v[24:25]
	v_pk_add_f32 v[2:3], v[2:3], v[20:21]
	s_cbranch_vccnz .LBB0_1767
	v_cvt_pk_bf16_f32 v20, v4, v5
	v_cvt_pk_bf16_f32 v21, v6, v7
	v_cvt_pk_bf16_f32 v22, v0, v1
	v_cvt_pk_bf16_f32 v23, v2, v3
	global_store_dwordx4 v[18:19], v[20:23], off offset:256
.LBB0_1767:
	v_pk_mul_f32 v[4:5], v[4:5], v[4:5]
	v_pk_mul_f32 v[6:7], v[6:7], v[6:7]
	v_pk_mul_f32 v[0:1], v[0:1], v[0:1]
	v_add_f32_e32 v6, v6, v7
	v_add_f32_e32 v4, v4, v5
	v_pk_mul_f32 v[2:3], v[2:3], v[2:3]
	v_add_f32_e32 v4, v4, v6
	v_add_f32_e32 v0, v0, v1
	v_pk_mul_f32 v[12:13], v[12:13], v[12:13]
	v_pk_mul_f32 v[14:15], v[14:15], v[14:15]
	v_add_f32_e32 v0, v0, v4
	v_add_f32_e32 v1, v2, v3
	v_pk_mul_f32 v[8:9], v[8:9], v[8:9]
	v_add_f32_e32 v0, v1, v0
	v_add_f32_e32 v1, v14, v15
	v_add_f32_e32 v2, v12, v13
	v_pk_mul_f32 v[10:11], v[10:11], v[10:11]
	v_add_f32_e32 v1, v2, v1
	v_add_f32_e32 v2, v8, v9
	v_add_f32_e32 v1, v2, v1
	v_add_f32_e32 v2, v10, v11
	v_add_f32_e32 v1, v2, v1
	v_add_f32_e32 v0, v1, v0
	ds_bpermute_b32 v1, v154, v0
	s_waitcnt lgkmcnt(0)
	v_add_f32_e32 v0, v0, v1
	ds_bpermute_b32 v1, v155, v0
	s_and_saveexec_b64 s[4:5], s[26:27]
	s_cbranch_execz .LBB0_1769
	v_readlane_b32 s44, v254, 8
	v_lshlrev_b64 v[2:3], 6, v[16:17]
	v_readlane_b32 s45, v254, 9
	s_lshl_b32 s42, s92, 2
	s_waitcnt lgkmcnt(0)
	v_add_f32_e32 v0, v0, v1
	v_lshl_add_u64 v[2:3], s[44:45], 0, v[2:3]
	v_lshl_add_u64 v[2:3], s[34:35], 2, v[2:3]
	v_lshl_add_u64 v[2:3], v[2:3], 0, s[42:43]
	global_store_dword v[2:3], v0, off

.LBB0_2309:
	v_lshl_or_b32 v138, s42, 8, v158
	v_lshl_add_u32 v140, s50, 8, v156
	v_ashrrev_i32_e32 v139, 31, v138
	v_ashrrev_i32_e32 v141, 31, v140
	v_readlane_b32 s4, v254, 6
	v_lshlrev_b64 v[142:143], 11, v[140:141]
	v_readlane_b32 s5, v254, 7
	s_andn2_b64 vcc, exec, s[8:9]
	s_nop 0
	v_lshl_add_u64 v[142:143], s[4:5], 0, v[142:143]
	v_lshl_add_u64 v[142:143], v[138:139], 1, v[142:143]
	v_mov_b32_e32 v166, v140
	v_ashrrev_i32_e32 v167, 31, v166
	v_lshlrev_b64 v[166:167], 11, v[166:167]
	v_lshl_add_u64 v[166:167], s[4:5], 0, v[166:167]
	v_lshl_add_u64 v[166:167], v[138:139], 1, v[166:167]
	global_load_dwordx4 v[188:191], v[166:167], off
	global_load_dwordx4 v[192:195], v[166:167], off offset:256
	v_add_u32_e32 v166, 16, v140
	v_ashrrev_i32_e32 v167, 31, v166
	v_lshlrev_b64 v[166:167], 11, v[166:167]
	v_lshl_add_u64 v[166:167], s[4:5], 0, v[166:167]
	v_lshl_add_u64 v[166:167], v[138:139], 1, v[166:167]
	global_load_dwordx4 v[196:199], v[166:167], off
	global_load_dwordx4 v[200:203], v[166:167], off offset:256
	v_add_u32_e32 v166, 32, v140
	v_ashrrev_i32_e32 v167, 31, v166
	v_lshlrev_b64 v[166:167], 11, v[166:167]
	v_lshl_add_u64 v[166:167], s[4:5], 0, v[166:167]
	v_lshl_add_u64 v[166:167], v[138:139], 1, v[166:167]
	global_load_dwordx4 v[204:207], v[166:167], off
	global_load_dwordx4 v[208:211], v[166:167], off offset:256
	v_add_u32_e32 v166, 48, v140
	v_ashrrev_i32_e32 v167, 31, v166
	v_lshlrev_b64 v[166:167], 11, v[166:167]
	v_lshl_add_u64 v[166:167], s[4:5], 0, v[166:167]
	v_lshl_add_u64 v[166:167], v[138:139], 1, v[166:167]
	global_load_dwordx4 v[212:215], v[166:167], off
	global_load_dwordx4 v[216:219], v[166:167], off offset:256
	v_add_u32_e32 v166, 128, v140
	v_ashrrev_i32_e32 v167, 31, v166
	v_lshlrev_b64 v[166:167], 11, v[166:167]
	v_lshl_add_u64 v[166:167], s[4:5], 0, v[166:167]
	v_lshl_add_u64 v[166:167], v[138:139], 1, v[166:167]
	global_load_dwordx4 v[220:223], v[166:167], off
	global_load_dwordx4 v[224:227], v[166:167], off offset:256
	v_add_u32_e32 v166, 144, v140
	v_ashrrev_i32_e32 v167, 31, v166
	v_lshlrev_b64 v[166:167], 11, v[166:167]
	v_lshl_add_u64 v[166:167], s[4:5], 0, v[166:167]
	v_lshl_add_u64 v[166:167], v[138:139], 1, v[166:167]
	global_load_dwordx4 v[228:231], v[166:167], off
	global_load_dwordx4 v[232:235], v[166:167], off offset:256
	s_waitcnt vmcnt(0)
	s_waitcnt lgkmcnt(0)
	v_lshlrev_b32_e32 v164, 16, v188
	v_and_b32_e32 v165, 0xffff0000, v188
	v_lshlrev_b32_e32 v160, 16, v189
	v_and_b32_e32 v161, 0xffff0000, v189
	v_pk_add_f32 v[126:127], v[126:127], v[160:161]
	v_lshlrev_b32_e32 v160, 16, v190
	v_and_b32_e32 v161, 0xffff0000, v190
	v_pk_add_f32 v[120:121], v[120:121], v[160:161]
	v_lshlrev_b32_e32 v160, 16, v191
	v_and_b32_e32 v161, 0xffff0000, v191
	v_pk_add_f32 v[122:123], v[122:123], v[160:161]
	v_cndmask_b32_e64 v160, 0, 1, s[8:9]
	v_pk_add_f32 v[124:125], v[124:125], v[164:165]
	v_cmp_ne_u32_e64 s[4:5], 1, v160
	s_cbranch_vccnz .LBB0_2311
	v_cvt_pk_bf16_f32 v160, v124, v125
	v_cvt_pk_bf16_f32 v161, v126, v127
	v_cvt_pk_bf16_f32 v162, v120, v121
	v_cvt_pk_bf16_f32 v163, v122, v123
	global_store_dwordx4 v[142:143], v[160:163], off
.LBB0_2311:
	s_and_b64 vcc, exec, s[4:5]
	s_waitcnt lgkmcnt(0)
	v_lshlrev_b32_e32 v164, 16, v192
	v_and_b32_e32 v165, 0xffff0000, v192
	v_lshlrev_b32_e32 v160, 16, v193
	v_and_b32_e32 v161, 0xffff0000, v193
	v_pk_add_f32 v[118:119], v[118:119], v[160:161]
	v_lshlrev_b32_e32 v160, 16, v194
	v_and_b32_e32 v161, 0xffff0000, v194
	v_pk_add_f32 v[112:113], v[112:113], v[160:161]
	v_lshlrev_b32_e32 v160, 16, v195
	v_and_b32_e32 v161, 0xffff0000, v195
	v_pk_add_f32 v[116:117], v[116:117], v[164:165]
	v_pk_add_f32 v[114:115], v[114:115], v[160:161]
	s_cbranch_vccnz .LBB0_2313
	v_cvt_pk_bf16_f32 v160, v116, v117
	v_cvt_pk_bf16_f32 v161, v118, v119
	v_cvt_pk_bf16_f32 v162, v112, v113
	v_cvt_pk_bf16_f32 v163, v114, v115
	global_store_dwordx4 v[142:143], v[160:163], off offset:256

.LBB0_2315:
	s_or_b64 exec, exec, s[44:45]
	v_or_b32_e32 v112, 16, v140
	s_waitcnt lgkmcnt(0)
	v_ashrrev_i32_e32 v113, 31, v112
	v_readlane_b32 s44, v254, 6
	v_lshlrev_b64 v[114:115], 11, v[112:113]
	v_readlane_b32 s45, v254, 7
	s_and_b64 vcc, exec, s[4:5]
	s_nop 0
	v_lshl_add_u64 v[114:115], s[44:45], 0, v[114:115]
	v_lshl_add_u64 v[114:115], v[138:139], 1, v[114:115]
	s_waitcnt lgkmcnt(0)
	v_lshlrev_b32_e32 v120, 16, v196
	v_and_b32_e32 v121, 0xffff0000, v196
	v_lshlrev_b32_e32 v116, 16, v197
	v_and_b32_e32 v117, 0xffff0000, v197
	v_pk_add_f32 v[110:111], v[110:111], v[116:117]
	v_lshlrev_b32_e32 v116, 16, v198
	v_and_b32_e32 v117, 0xffff0000, v198
	v_pk_add_f32 v[104:105], v[104:105], v[116:117]
	v_lshlrev_b32_e32 v116, 16, v199
	v_and_b32_e32 v117, 0xffff0000, v199
	v_pk_add_f32 v[108:109], v[108:109], v[120:121]
	v_pk_add_f32 v[106:107], v[106:107], v[116:117]
	s_cbranch_vccnz .LBB0_2317
	v_cvt_pk_bf16_f32 v116, v108, v109
	v_cvt_pk_bf16_f32 v117, v110, v111
	v_cvt_pk_bf16_f32 v118, v104, v105
	v_cvt_pk_bf16_f32 v119, v106, v107
	global_store_dwordx4 v[114:115], v[116:119], off
.LBB0_2317:
	s_and_b64 vcc, exec, s[4:5]
	s_waitcnt lgkmcnt(0)
	v_lshlrev_b32_e32 v120, 16, v200
	v_and_b32_e32 v121, 0xffff0000, v200
	v_lshlrev_b32_e32 v116, 16, v201
	v_and_b32_e32 v117, 0xffff0000, v201
	v_pk_add_f32 v[102:103], v[102:103], v[116:117]
	v_lshlrev_b32_e32 v116, 16, v202
	v_and_b32_e32 v117, 0xffff0000, v202
	v_pk_add_f32 v[96:97], v[96:97], v[116:117]
	v_lshlrev_b32_e32 v116, 16, v203
	v_and_b32_e32 v117, 0xffff0000, v203
	v_pk_add_f32 v[100:101], v[100:101], v[120:121]
	v_pk_add_f32 v[98:99], v[98:99], v[116:117]
	s_cbranch_vccnz .LBB0_2319
	v_cvt_pk_bf16_f32 v116, v100, v101
	v_cvt_pk_bf16_f32 v117, v102, v103
	v_cvt_pk_bf16_f32 v118, v96, v97
	v_cvt_pk_bf16_f32 v119, v98, v99
	global_store_dwordx4 v[114:115], v[116:119], off offset:256

.LBB0_2321:
	s_or_b64 exec, exec, s[44:45]
	v_or_b32_e32 v96, 32, v140
	s_waitcnt lgkmcnt(0)
	v_ashrrev_i32_e32 v97, 31, v96
	v_readlane_b32 s44, v254, 6
	v_lshlrev_b64 v[98:99], 11, v[96:97]
	v_readlane_b32 s45, v254, 7
	s_and_b64 vcc, exec, s[4:5]
	s_nop 0
	v_lshl_add_u64 v[98:99], s[44:45], 0, v[98:99]
	v_lshl_add_u64 v[98:99], v[138:139], 1, v[98:99]
	s_waitcnt lgkmcnt(0)
	v_lshlrev_b32_e32 v104, 16, v204
	v_and_b32_e32 v105, 0xffff0000, v204
	v_lshlrev_b32_e32 v100, 16, v205
	v_and_b32_e32 v101, 0xffff0000, v205
	v_pk_add_f32 v[94:95], v[94:95], v[100:101]
	v_lshlrev_b32_e32 v100, 16, v206
	v_and_b32_e32 v101, 0xffff0000, v206
	v_pk_add_f32 v[88:89], v[88:89], v[100:101]
	v_lshlrev_b32_e32 v100, 16, v207
	v_and_b32_e32 v101, 0xffff0000, v207
	v_pk_add_f32 v[92:93], v[92:93], v[104:105]
	v_pk_add_f32 v[90:91], v[90:91], v[100:101]
	s_cbranch_vccnz .LBB0_2323
	v_cvt_pk_bf16_f32 v100, v92, v93
	v_cvt_pk_bf16_f32 v101, v94, v95
	v_cvt_pk_bf16_f32 v102, v88, v89
	v_cvt_pk_bf16_f32 v103, v90, v91
	global_store_dwordx4 v[98:99], v[100:103], off
.LBB0_2323:
	s_and_b64 vcc, exec, s[4:5]
	s_waitcnt lgkmcnt(0)
	v_lshlrev_b32_e32 v104, 16, v208
	v_and_b32_e32 v105, 0xffff0000, v208
	v_lshlrev_b32_e32 v100, 16, v209
	v_and_b32_e32 v101, 0xffff0000, v209
	v_pk_add_f32 v[86:87], v[86:87], v[100:101]
	v_lshlrev_b32_e32 v100, 16, v210
	v_and_b32_e32 v101, 0xffff0000, v210
	v_pk_add_f32 v[80:81], v[80:81], v[100:101]
	v_lshlrev_b32_e32 v100, 16, v211
	v_and_b32_e32 v101, 0xffff0000, v211
	v_pk_add_f32 v[84:85], v[84:85], v[104:105]
	v_pk_add_f32 v[82:83], v[82:83], v[100:101]
	s_cbranch_vccnz .LBB0_2325
	v_cvt_pk_bf16_f32 v100, v84, v85
	v_cvt_pk_bf16_f32 v101, v86, v87
	v_cvt_pk_bf16_f32 v102, v80, v81
	v_cvt_pk_bf16_f32 v103, v82, v83
	global_store_dwordx4 v[98:99], v[100:103], off offset:256

.LBB0_2327:
	s_or_b64 exec, exec, s[44:45]
	v_or_b32_e32 v80, 48, v140
	s_waitcnt lgkmcnt(0)
	v_ashrrev_i32_e32 v81, 31, v80
	v_readlane_b32 s44, v254, 6
	v_lshlrev_b64 v[82:83], 11, v[80:81]
	v_readlane_b32 s45, v254, 7
	s_and_b64 vcc, exec, s[4:5]
	s_nop 0
	v_lshl_add_u64 v[82:83], s[44:45], 0, v[82:83]
	v_lshl_add_u64 v[82:83], v[138:139], 1, v[82:83]
	s_waitcnt lgkmcnt(0)
	v_lshlrev_b32_e32 v88, 16, v212
	v_and_b32_e32 v89, 0xffff0000, v212
	v_lshlrev_b32_e32 v84, 16, v213
	v_and_b32_e32 v85, 0xffff0000, v213
	v_pk_add_f32 v[78:79], v[78:79], v[84:85]
	v_lshlrev_b32_e32 v84, 16, v214
	v_and_b32_e32 v85, 0xffff0000, v214
	v_pk_add_f32 v[72:73], v[72:73], v[84:85]
	v_lshlrev_b32_e32 v84, 16, v215
	v_and_b32_e32 v85, 0xffff0000, v215
	v_pk_add_f32 v[76:77], v[76:77], v[88:89]
	v_pk_add_f32 v[74:75], v[74:75], v[84:85]
	s_cbranch_vccnz .LBB0_2329
	v_cvt_pk_bf16_f32 v84, v76, v77
	v_cvt_pk_bf16_f32 v85, v78, v79
	v_cvt_pk_bf16_f32 v86, v72, v73
	v_cvt_pk_bf16_f32 v87, v74, v75
	global_store_dwordx4 v[82:83], v[84:87], off
.LBB0_2329:
	s_and_b64 vcc, exec, s[4:5]
	s_waitcnt lgkmcnt(0)
	v_lshlrev_b32_e32 v88, 16, v216
	v_and_b32_e32 v89, 0xffff0000, v216
	v_lshlrev_b32_e32 v84, 16, v217
	v_and_b32_e32 v85, 0xffff0000, v217
	v_pk_add_f32 v[70:71], v[70:71], v[84:85]
	v_lshlrev_b32_e32 v84, 16, v218
	v_and_b32_e32 v85, 0xffff0000, v218
	v_pk_add_f32 v[64:65], v[64:65], v[84:85]
	v_lshlrev_b32_e32 v84, 16, v219
	v_and_b32_e32 v85, 0xffff0000, v219
	v_pk_add_f32 v[68:69], v[68:69], v[88:89]
	v_pk_add_f32 v[66:67], v[66:67], v[84:85]
	s_cbranch_vccnz .LBB0_2331
	v_cvt_pk_bf16_f32 v84, v68, v69
	v_cvt_pk_bf16_f32 v85, v70, v71
	v_cvt_pk_bf16_f32 v86, v64, v65
	v_cvt_pk_bf16_f32 v87, v66, v67
	global_store_dwordx4 v[82:83], v[84:87], off offset:256

.LBB0_2333:
	s_or_b64 exec, exec, s[44:45]
	v_add_u32_e32 v64, 0x80, v140
	s_waitcnt lgkmcnt(0)
	v_ashrrev_i32_e32 v65, 31, v64
	v_readlane_b32 s44, v254, 6
	v_lshlrev_b64 v[66:67], 11, v[64:65]
	v_readlane_b32 s45, v254, 7
	s_and_b64 vcc, exec, s[4:5]
	s_nop 0
	v_lshl_add_u64 v[66:67], s[44:45], 0, v[66:67]
	v_lshl_add_u64 v[66:67], v[138:139], 1, v[66:67]
	v_add_u32_e32 v166, 160, v140
	v_ashrrev_i32_e32 v167, 31, v166
	v_lshlrev_b64 v[166:167], 11, v[166:167]
	v_lshl_add_u64 v[166:167], s[44:45], 0, v[166:167]
	v_lshl_add_u64 v[166:167], v[138:139], 1, v[166:167]
	global_load_dwordx4 v[188:191], v[166:167], off
	global_load_dwordx4 v[192:195], v[166:167], off offset:256
	v_add_u32_e32 v166, 176, v140
	v_ashrrev_i32_e32 v167, 31, v166
	v_lshlrev_b64 v[166:167], 11, v[166:167]
	v_lshl_add_u64 v[166:167], s[44:45], 0, v[166:167]
	v_lshl_add_u64 v[166:167], v[138:139], 1, v[166:167]
	global_load_dwordx4 v[196:199], v[166:167], off
	global_load_dwordx4 v[200:203], v[166:167], off offset:256
	s_waitcnt lgkmcnt(0)
	v_lshlrev_b32_e32 v72, 16, v220
	v_and_b32_e32 v73, 0xffff0000, v220
	v_lshlrev_b32_e32 v68, 16, v221
	v_and_b32_e32 v69, 0xffff0000, v221
	v_pk_add_f32 v[62:63], v[62:63], v[68:69]
	v_lshlrev_b32_e32 v68, 16, v222
	v_and_b32_e32 v69, 0xffff0000, v222
	v_pk_add_f32 v[56:57], v[56:57], v[68:69]
	v_lshlrev_b32_e32 v68, 16, v223
	v_and_b32_e32 v69, 0xffff0000, v223
	v_pk_add_f32 v[60:61], v[60:61], v[72:73]
	v_pk_add_f32 v[58:59], v[58:59], v[68:69]
	s_cbranch_vccnz .LBB0_2335
	v_cvt_pk_bf16_f32 v68, v60, v61
	v_cvt_pk_bf16_f32 v69, v62, v63
	v_cvt_pk_bf16_f32 v70, v56, v57
	v_cvt_pk_bf16_f32 v71, v58, v59
	global_store_dwordx4 v[66:67], v[68:71], off
.LBB0_2335:
	s_and_b64 vcc, exec, s[4:5]
	s_waitcnt lgkmcnt(0)
	v_lshlrev_b32_e32 v72, 16, v224
	v_and_b32_e32 v73, 0xffff0000, v224
	v_lshlrev_b32_e32 v68, 16, v225
	v_and_b32_e32 v69, 0xffff0000, v225
	v_pk_add_f32 v[54:55], v[54:55], v[68:69]
	v_lshlrev_b32_e32 v68, 16, v226
	v_and_b32_e32 v69, 0xffff0000, v226
	v_pk_add_f32 v[48:49], v[48:49], v[68:69]
	v_lshlrev_b32_e32 v68, 16, v227
	v_and_b32_e32 v69, 0xffff0000, v227
	v_pk_add_f32 v[52:53], v[52:53], v[72:73]
	v_pk_add_f32 v[50:51], v[50:51], v[68:69]
	s_cbranch_vccnz .LBB0_2337
	v_cvt_pk_bf16_f32 v68, v52, v53
	v_cvt_pk_bf16_f32 v69, v54, v55
	v_cvt_pk_bf16_f32 v70, v48, v49
	v_cvt_pk_bf16_f32 v71, v50, v51
	global_store_dwordx4 v[66:67], v[68:71], off offset:256

.LBB0_2339:
	s_or_b64 exec, exec, s[44:45]
	v_add_u32_e32 v48, 0x90, v140
	s_waitcnt lgkmcnt(0)
	v_ashrrev_i32_e32 v49, 31, v48
	v_readlane_b32 s44, v254, 6
	v_lshlrev_b64 v[50:51], 11, v[48:49]
	v_readlane_b32 s45, v254, 7
	s_and_b64 vcc, exec, s[4:5]
	s_nop 0
	v_lshl_add_u64 v[50:51], s[44:45], 0, v[50:51]
	v_lshl_add_u64 v[50:51], v[138:139], 1, v[50:51]
	s_waitcnt lgkmcnt(0)
	v_lshlrev_b32_e32 v56, 16, v228
	v_and_b32_e32 v57, 0xffff0000, v228
	v_lshlrev_b32_e32 v52, 16, v229
	v_and_b32_e32 v53, 0xffff0000, v229
	v_pk_add_f32 v[46:47], v[46:47], v[52:53]
	v_lshlrev_b32_e32 v52, 16, v230
	v_and_b32_e32 v53, 0xffff0000, v230
	v_pk_add_f32 v[40:41], v[40:41], v[52:53]
	v_lshlrev_b32_e32 v52, 16, v231
	v_and_b32_e32 v53, 0xffff0000, v231
	v_pk_add_f32 v[44:45], v[44:45], v[56:57]
	v_pk_add_f32 v[42:43], v[42:43], v[52:53]
	s_cbranch_vccnz .LBB0_2341
	v_cvt_pk_bf16_f32 v52, v44, v45
	v_cvt_pk_bf16_f32 v53, v46, v47
	v_cvt_pk_bf16_f32 v54, v40, v41
	v_cvt_pk_bf16_f32 v55, v42, v43
	global_store_dwordx4 v[50:51], v[52:55], off
.LBB0_2341:
	s_and_b64 vcc, exec, s[4:5]
	s_waitcnt lgkmcnt(0)
	v_lshlrev_b32_e32 v56, 16, v232
	v_and_b32_e32 v57, 0xffff0000, v232
	v_lshlrev_b32_e32 v52, 16, v233
	v_and_b32_e32 v53, 0xffff0000, v233
	v_pk_add_f32 v[38:39], v[38:39], v[52:53]
	v_lshlrev_b32_e32 v52, 16, v234
	v_and_b32_e32 v53, 0xffff0000, v234
	v_pk_add_f32 v[32:33], v[32:33], v[52:53]
	v_lshlrev_b32_e32 v52, 16, v235
	v_and_b32_e32 v53, 0xffff0000, v235
	v_pk_add_f32 v[36:37], v[36:37], v[56:57]
	v_pk_add_f32 v[34:35], v[34:35], v[52:53]
	s_cbranch_vccnz .LBB0_2343
	v_cvt_pk_bf16_f32 v52, v36, v37
	v_cvt_pk_bf16_f32 v53, v38, v39
	v_cvt_pk_bf16_f32 v54, v32, v33
	v_cvt_pk_bf16_f32 v55, v34, v35
	global_store_dwordx4 v[50:51], v[52:55], off offset:256

.LBB0_2345:
	s_or_b64 exec, exec, s[44:45]
	v_add_u32_e32 v32, 0xa0, v140
	s_waitcnt lgkmcnt(0)
	v_ashrrev_i32_e32 v33, 31, v32
	v_readlane_b32 s44, v254, 6
	v_lshlrev_b64 v[34:35], 11, v[32:33]
	v_readlane_b32 s45, v254, 7
	s_and_b64 vcc, exec, s[4:5]
	s_nop 0
	v_lshl_add_u64 v[34:35], s[44:45], 0, v[34:35]
	v_lshl_add_u64 v[34:35], v[138:139], 1, v[34:35]
	s_waitcnt vmcnt(0)
	s_waitcnt lgkmcnt(0)
	v_lshlrev_b32_e32 v40, 16, v188
	v_and_b32_e32 v41, 0xffff0000, v188
	v_lshlrev_b32_e32 v36, 16, v189
	v_and_b32_e32 v37, 0xffff0000, v189
	v_pk_add_f32 v[30:31], v[30:31], v[36:37]
	v_lshlrev_b32_e32 v36, 16, v190
	v_and_b32_e32 v37, 0xffff0000, v190
	v_pk_add_f32 v[24:25], v[24:25], v[36:37]
	v_lshlrev_b32_e32 v36, 16, v191
	v_and_b32_e32 v37, 0xffff0000, v191
	v_pk_add_f32 v[28:29], v[28:29], v[40:41]
	v_pk_add_f32 v[26:27], v[26:27], v[36:37]
	s_cbranch_vccnz .LBB0_2347
	v_cvt_pk_bf16_f32 v36, v28, v29
	v_cvt_pk_bf16_f32 v37, v30, v31
	v_cvt_pk_bf16_f32 v38, v24, v25
	v_cvt_pk_bf16_f32 v39, v26, v27
	global_store_dwordx4 v[34:35], v[36:39], off
.LBB0_2347:
	s_and_b64 vcc, exec, s[4:5]
	s_waitcnt lgkmcnt(0)
	v_lshlrev_b32_e32 v40, 16, v192
	v_and_b32_e32 v41, 0xffff0000, v192
	v_lshlrev_b32_e32 v36, 16, v193
	v_and_b32_e32 v37, 0xffff0000, v193
	v_pk_add_f32 v[22:23], v[22:23], v[36:37]
	v_lshlrev_b32_e32 v36, 16, v194
	v_and_b32_e32 v37, 0xffff0000, v194
	v_pk_add_f32 v[16:17], v[16:17], v[36:37]
	v_lshlrev_b32_e32 v36, 16, v195
	v_and_b32_e32 v37, 0xffff0000, v195
	v_pk_add_f32 v[20:21], v[20:21], v[40:41]
	v_pk_add_f32 v[18:19], v[18:19], v[36:37]
	s_cbranch_vccnz .LBB0_2349
	v_cvt_pk_bf16_f32 v36, v20, v21
	v_cvt_pk_bf16_f32 v37, v22, v23
	v_cvt_pk_bf16_f32 v38, v16, v17
	v_cvt_pk_bf16_f32 v39, v18, v19
	global_store_dwordx4 v[34:35], v[36:39], off offset:256

.LBB0_2351:
	s_or_b64 exec, exec, s[44:45]
	v_add_u32_e32 v16, 0xb0, v140
	s_waitcnt lgkmcnt(0)
	v_ashrrev_i32_e32 v17, 31, v16
	v_readlane_b32 s44, v254, 6
	v_lshlrev_b64 v[18:19], 11, v[16:17]
	v_readlane_b32 s45, v254, 7
	s_and_b64 vcc, exec, s[4:5]
	s_nop 0
	v_lshl_add_u64 v[18:19], s[44:45], 0, v[18:19]
	v_lshl_add_u64 v[18:19], v[138:139], 1, v[18:19]
	s_waitcnt lgkmcnt(0)
	v_lshlrev_b32_e32 v24, 16, v196
	v_and_b32_e32 v25, 0xffff0000, v196
	v_lshlrev_b32_e32 v20, 16, v197
	v_and_b32_e32 v21, 0xffff0000, v197
	v_pk_add_f32 v[14:15], v[14:15], v[20:21]
	v_lshlrev_b32_e32 v20, 16, v198
	v_and_b32_e32 v21, 0xffff0000, v198
	v_pk_add_f32 v[8:9], v[8:9], v[20:21]
	v_lshlrev_b32_e32 v20, 16, v199
	v_and_b32_e32 v21, 0xffff0000, v199
	v_pk_add_f32 v[12:13], v[12:13], v[24:25]
	v_pk_add_f32 v[10:11], v[10:11], v[20:21]
	s_cbranch_vccnz .LBB0_2353
	v_cvt_pk_bf16_f32 v20, v12, v13
	v_cvt_pk_bf16_f32 v21, v14, v15
	v_cvt_pk_bf16_f32 v22, v8, v9
	v_cvt_pk_bf16_f32 v23, v10, v11
	global_store_dwordx4 v[18:19], v[20:23], off
.LBB0_2353:
	s_and_b64 vcc, exec, s[4:5]
	s_movk_i32 s51, 0x200
	s_waitcnt lgkmcnt(0)
	v_lshlrev_b32_e32 v24, 16, v200
	v_and_b32_e32 v25, 0xffff0000, v200
	v_lshlrev_b32_e32 v20, 16, v201
	v_and_b32_e32 v21, 0xffff0000, v201
	v_pk_add_f32 v[6:7], v[6:7], v[20:21]
	v_lshlrev_b32_e32 v20, 16, v202
	v_and_b32_e32 v21, 0xffff0000, v202
	v_pk_add_f32 v[0:1], v[0:1], v[20:21]
	v_lshlrev_b32_e32 v20, 16, v203
	v_and_b32_e32 v21, 0xffff0000, v203
	v_pk_add_f32 v[4:5], v[4:5], v[24:25]
	v_pk_add_f32 v[2:3], v[2:3], v[20:21]
	s_cbranch_vccnz .LBB0_2355
	v_cvt_pk_bf16_f32 v20, v4, v5
	v_cvt_pk_bf16_f32 v21, v6, v7
	v_cvt_pk_bf16_f32 v22, v0, v1
	v_cvt_pk_bf16_f32 v23, v2, v3
	global_store_dwordx4 v[18:19], v[20:23], off offset:256

.LBB0_2969:
	v_lshl_or_b32 v138, s42, 8, v160
	v_lshl_add_u32 v140, s48, 8, v158
	v_ashrrev_i32_e32 v139, 31, v138
	v_ashrrev_i32_e32 v141, 31, v140
	v_lshlrev_b64 v[142:143], 10, v[140:141]
	v_readlane_b32 s4, v254, 6
	v_lshl_add_u64 v[142:143], v[142:143], 0, v[138:139]
	v_readlane_b32 s5, v254, 7
	v_readlane_b32 s6, v254, 58
	v_readlane_b32 s7, v254, 59
	v_lshl_add_u64 v[154:155], v[142:143], 1, s[4:5]
	v_mov_b32_e32 v234, v140
	v_ashrrev_i32_e32 v235, 31, v234
	v_lshlrev_b64 v[234:235], 11, v[234:235]
	v_lshl_add_u64 v[234:235], s[4:5], 0, v[234:235]
	v_lshl_add_u64 v[234:235], v[138:139], 1, v[234:235]
	global_load_dwordx4 v[186:189], v[234:235], off
	global_load_dwordx4 v[190:193], v[234:235], off offset:256
	v_add_u32_e32 v234, 16, v140
	v_ashrrev_i32_e32 v235, 31, v234
	v_lshlrev_b64 v[234:235], 11, v[234:235]
	v_lshl_add_u64 v[234:235], s[4:5], 0, v[234:235]
	v_lshl_add_u64 v[234:235], v[138:139], 1, v[234:235]
	global_load_dwordx4 v[194:197], v[234:235], off
	global_load_dwordx4 v[198:201], v[234:235], off offset:256
	v_add_u32_e32 v234, 32, v140
	v_ashrrev_i32_e32 v235, 31, v234
	v_lshlrev_b64 v[234:235], 11, v[234:235]
	v_lshl_add_u64 v[234:235], s[4:5], 0, v[234:235]
	v_lshl_add_u64 v[234:235], v[138:139], 1, v[234:235]
	global_load_dwordx4 v[202:205], v[234:235], off
	global_load_dwordx4 v[206:209], v[234:235], off offset:256
	v_add_u32_e32 v234, 48, v140
	v_ashrrev_i32_e32 v235, 31, v234
	v_lshlrev_b64 v[234:235], 11, v[234:235]
	v_lshl_add_u64 v[234:235], s[4:5], 0, v[234:235]
	v_lshl_add_u64 v[234:235], v[138:139], 1, v[234:235]
	global_load_dwordx4 v[210:213], v[234:235], off
	global_load_dwordx4 v[214:217], v[234:235], off offset:256
	v_add_u32_e32 v234, 128, v140
	v_ashrrev_i32_e32 v235, 31, v234
	v_lshlrev_b64 v[234:235], 11, v[234:235]
	v_lshl_add_u64 v[234:235], s[4:5], 0, v[234:235]
	v_lshl_add_u64 v[234:235], v[138:139], 1, v[234:235]
	global_load_dwordx4 v[218:221], v[234:235], off
	global_load_dwordx4 v[222:225], v[234:235], off offset:256
	v_add_u32_e32 v234, 144, v140
	v_ashrrev_i32_e32 v235, 31, v234
	v_lshlrev_b64 v[234:235], 11, v[234:235]
	v_lshl_add_u64 v[234:235], s[4:5], 0, v[234:235]
	v_lshl_add_u64 v[234:235], v[138:139], 1, v[234:235]
	global_load_dwordx4 v[226:229], v[234:235], off
	global_load_dwordx4 v[230:233], v[234:235], off offset:256
	s_waitcnt vmcnt(0)
	s_andn2_b64 vcc, exec, s[10:11]
	s_waitcnt lgkmcnt(0)
	v_lshlrev_b32_e32 v166, 16, v186
	v_and_b32_e32 v167, 0xffff0000, v186
	v_lshlrev_b32_e32 v162, 16, v187
	v_and_b32_e32 v163, 0xffff0000, v187
	v_pk_add_f32 v[126:127], v[126:127], v[162:163]
	v_lshlrev_b32_e32 v162, 16, v188
	v_and_b32_e32 v163, 0xffff0000, v188
	v_pk_add_f32 v[120:121], v[120:121], v[162:163]
	v_lshlrev_b32_e32 v162, 16, v189
	v_and_b32_e32 v163, 0xffff0000, v189
	v_pk_add_f32 v[122:123], v[122:123], v[162:163]
	v_cndmask_b32_e64 v162, 0, 1, s[10:11]
	v_cmp_ne_u32_e64 s[4:5], 1, v162
	v_cndmask_b32_e64 v162, 0, 1, s[6:7]
	v_pk_add_f32 v[124:125], v[124:125], v[166:167]
	v_cmp_ne_u32_e64 s[6:7], 1, v162
	s_cbranch_vccnz .LBB0_2973
	s_and_b64 vcc, exec, s[6:7]
	s_cbranch_vccnz .LBB0_2972
	v_lshl_add_u64 v[162:163], v[142:143], 2, s[44:45]
	global_store_dwordx4 v[162:163], v[124:127], off
	global_store_dwordx4 v[162:163], v[120:123], off offset:16
.LBB0_2972:
	v_cvt_pk_bf16_f32 v162, v124, v125
	v_cvt_pk_bf16_f32 v163, v126, v127
	v_cvt_pk_bf16_f32 v164, v120, v121
	v_cvt_pk_bf16_f32 v165, v122, v123
	global_store_dwordx4 v[154:155], v[162:165], off
.LBB0_2973:
	v_lshlrev_b64 v[154:155], 1, v[142:143]
	v_readlane_b32 s46, v254, 6
	v_or_b32_e32 v154, 0x100, v154
	v_readlane_b32 s47, v254, 7
	s_and_b64 vcc, exec, s[4:5]
	s_nop 0
	v_lshl_add_u64 v[154:155], s[46:47], 0, v[154:155]
	s_waitcnt lgkmcnt(0)
	v_lshlrev_b32_e32 v166, 16, v190
	v_and_b32_e32 v167, 0xffff0000, v190
	v_lshlrev_b32_e32 v162, 16, v191
	v_and_b32_e32 v163, 0xffff0000, v191
	v_pk_add_f32 v[118:119], v[118:119], v[162:163]
	v_lshlrev_b32_e32 v162, 16, v192
	v_and_b32_e32 v163, 0xffff0000, v192
	v_pk_add_f32 v[112:113], v[112:113], v[162:163]
	v_lshlrev_b32_e32 v162, 16, v193
	v_and_b32_e32 v163, 0xffff0000, v193
	v_pk_add_f32 v[116:117], v[116:117], v[166:167]
	v_pk_add_f32 v[114:115], v[114:115], v[162:163]
	s_cbranch_vccnz .LBB0_2977
	s_and_b64 vcc, exec, s[6:7]
	s_cbranch_vccnz .LBB0_2976
	v_lshl_add_u64 v[142:143], v[142:143], 2, s[44:45]
	global_store_dwordx4 v[142:143], v[116:119], off offset:512
	global_store_dwordx4 v[142:143], v[112:115], off offset:528
.LBB0_2976:
	v_cvt_pk_bf16_f32 v162, v116, v117
	v_cvt_pk_bf16_f32 v163, v118, v119
	v_cvt_pk_bf16_f32 v164, v112, v113
	v_cvt_pk_bf16_f32 v165, v114, v115
	global_store_dwordx4 v[154:155], v[162:165], off
.LBB0_2977:
	v_pk_mul_f32 v[116:117], v[116:117], v[116:117]
	v_pk_mul_f32 v[118:119], v[118:119], v[118:119]
	v_pk_mul_f32 v[112:113], v[112:113], v[112:113]
	v_add_f32_e32 v118, v118, v119
	v_add_f32_e32 v116, v116, v117
	v_pk_mul_f32 v[114:115], v[114:115], v[114:115]
	v_add_f32_e32 v116, v116, v118
	v_add_f32_e32 v112, v112, v113
	v_pk_mul_f32 v[124:125], v[124:125], v[124:125]
	v_pk_mul_f32 v[126:127], v[126:127], v[126:127]
	v_add_f32_e32 v112, v112, v116
	v_add_f32_e32 v113, v114, v115
	v_pk_mul_f32 v[120:121], v[120:121], v[120:121]
	v_add_f32_e32 v112, v113, v112
	v_add_f32_e32 v113, v126, v127
	v_add_f32_e32 v114, v124, v125
	v_pk_mul_f32 v[122:123], v[122:123], v[122:123]
	v_add_f32_e32 v113, v114, v113
	v_add_f32_e32 v114, v120, v121
	v_add_f32_e32 v113, v114, v113
	v_add_f32_e32 v114, v122, v123
	v_add_f32_e32 v113, v114, v113
	v_add_f32_e32 v112, v113, v112
	ds_bpermute_b32 v113, v156, v112
	s_lshl_b32 s56, s42, 2
	s_ashr_i32 s57, s56, 31
	s_waitcnt lgkmcnt(0)
	v_add_f32_e32 v112, v112, v113
	ds_bpermute_b32 v113, v157, v112
	s_and_saveexec_b64 s[46:47], s[28:29]
	s_cbranch_execz .LBB0_2979
	v_readlane_b32 s48, v254, 8
	v_lshlrev_b64 v[114:115], 6, v[140:141]
	v_readlane_b32 s49, v254, 9
	s_lshl_b32 s42, s18, 2
	s_waitcnt lgkmcnt(0)
	v_add_f32_e32 v112, v112, v113
	v_lshl_add_u64 v[114:115], s[48:49], 0, v[114:115]
	v_lshl_add_u64 v[114:115], s[56:57], 2, v[114:115]
	v_lshl_add_u64 v[114:115], v[114:115], 0, s[42:43]
	global_store_dword v[114:115], v112, off
.LBB0_2979:
	s_or_b64 exec, exec, s[46:47]
	v_or_b32_e32 v112, 16, v140
	s_waitcnt lgkmcnt(0)
	v_ashrrev_i32_e32 v113, 31, v112
	v_lshlrev_b64 v[114:115], 10, v[112:113]
	v_readlane_b32 s46, v254, 6
	v_lshl_add_u64 v[114:115], v[114:115], 0, v[138:139]
	v_readlane_b32 s47, v254, 7
	s_and_b64 vcc, exec, s[4:5]
	s_nop 0
	v_lshl_add_u64 v[116:117], v[114:115], 1, s[46:47]
	s_waitcnt lgkmcnt(0)
	v_lshlrev_b32_e32 v122, 16, v194
	v_and_b32_e32 v123, 0xffff0000, v194
	v_lshlrev_b32_e32 v118, 16, v195
	v_and_b32_e32 v119, 0xffff0000, v195
	v_pk_add_f32 v[110:111], v[110:111], v[118:119]
	v_lshlrev_b32_e32 v118, 16, v196
	v_and_b32_e32 v119, 0xffff0000, v196
	v_pk_add_f32 v[104:105], v[104:105], v[118:119]
	v_lshlrev_b32_e32 v118, 16, v197
	v_and_b32_e32 v119, 0xffff0000, v197
	v_pk_add_f32 v[108:109], v[108:109], v[122:123]
	v_pk_add_f32 v[106:107], v[106:107], v[118:119]
	s_cbranch_vccnz .LBB0_2983
	s_and_b64 vcc, exec, s[6:7]
	s_cbranch_vccnz .LBB0_2982
	v_lshl_add_u64 v[118:119], v[114:115], 2, s[44:45]
	global_store_dwordx4 v[118:119], v[108:111], off
	global_store_dwordx4 v[118:119], v[104:107], off offset:16
.LBB0_2982:
	v_cvt_pk_bf16_f32 v118, v108, v109
	v_cvt_pk_bf16_f32 v119, v110, v111
	v_cvt_pk_bf16_f32 v120, v104, v105
	v_cvt_pk_bf16_f32 v121, v106, v107
	global_store_dwordx4 v[116:117], v[118:121], off
.LBB0_2983:
	v_lshlrev_b64 v[116:117], 1, v[114:115]
	v_readlane_b32 s46, v254, 6
	v_or_b32_e32 v116, 0x100, v116
	v_readlane_b32 s47, v254, 7
	s_and_b64 vcc, exec, s[4:5]
	s_nop 0
	v_lshl_add_u64 v[116:117], s[46:47], 0, v[116:117]
	s_waitcnt lgkmcnt(0)
	v_lshlrev_b32_e32 v122, 16, v198
	v_and_b32_e32 v123, 0xffff0000, v198
	v_lshlrev_b32_e32 v118, 16, v199
	v_and_b32_e32 v119, 0xffff0000, v199
	v_pk_add_f32 v[102:103], v[102:103], v[118:119]
	v_lshlrev_b32_e32 v118, 16, v200
	v_and_b32_e32 v119, 0xffff0000, v200
	v_pk_add_f32 v[96:97], v[96:97], v[118:119]
	v_lshlrev_b32_e32 v118, 16, v201
	v_and_b32_e32 v119, 0xffff0000, v201
	v_pk_add_f32 v[100:101], v[100:101], v[122:123]
	v_pk_add_f32 v[98:99], v[98:99], v[118:119]
	s_cbranch_vccnz .LBB0_2987
	s_and_b64 vcc, exec, s[6:7]
	s_cbranch_vccnz .LBB0_2986
	v_lshl_add_u64 v[114:115], v[114:115], 2, s[44:45]
	global_store_dwordx4 v[114:115], v[100:103], off offset:512
	global_store_dwordx4 v[114:115], v[96:99], off offset:528
.LBB0_2986:
	v_cvt_pk_bf16_f32 v118, v100, v101
	v_cvt_pk_bf16_f32 v119, v102, v103
	v_cvt_pk_bf16_f32 v120, v96, v97
	v_cvt_pk_bf16_f32 v121, v98, v99
	global_store_dwordx4 v[116:117], v[118:121], off
.LBB0_2987:
	v_pk_mul_f32 v[100:101], v[100:101], v[100:101]
	v_pk_mul_f32 v[102:103], v[102:103], v[102:103]
	v_pk_mul_f32 v[96:97], v[96:97], v[96:97]
	v_add_f32_e32 v102, v102, v103
	v_add_f32_e32 v100, v100, v101
	v_pk_mul_f32 v[98:99], v[98:99], v[98:99]
	v_add_f32_e32 v100, v100, v102
	v_add_f32_e32 v96, v96, v97
	v_pk_mul_f32 v[108:109], v[108:109], v[108:109]
	v_pk_mul_f32 v[110:111], v[110:111], v[110:111]
	v_add_f32_e32 v96, v96, v100
	v_add_f32_e32 v97, v98, v99
	v_pk_mul_f32 v[104:105], v[104:105], v[104:105]
	v_add_f32_e32 v96, v97, v96
	v_add_f32_e32 v97, v110, v111
	v_add_f32_e32 v98, v108, v109
	v_pk_mul_f32 v[106:107], v[106:107], v[106:107]
	v_add_f32_e32 v97, v98, v97
	v_add_f32_e32 v98, v104, v105
	v_add_f32_e32 v97, v98, v97
	v_add_f32_e32 v98, v106, v107
	v_add_f32_e32 v97, v98, v97
	v_add_f32_e32 v96, v97, v96
	ds_bpermute_b32 v97, v156, v96
	s_waitcnt lgkmcnt(0)
	v_add_f32_e32 v96, v96, v97
	ds_bpermute_b32 v97, v157, v96
	s_and_saveexec_b64 s[46:47], s[28:29]
	s_cbranch_execz .LBB0_2989
	v_readlane_b32 s48, v254, 8
	v_lshlrev_b64 v[98:99], 6, v[112:113]
	v_readlane_b32 s49, v254, 9
	s_lshl_b32 s42, s18, 2
	s_waitcnt lgkmcnt(0)
	v_add_f32_e32 v96, v96, v97
	v_lshl_add_u64 v[98:99], s[48:49], 0, v[98:99]
	v_lshl_add_u64 v[98:99], s[56:57], 2, v[98:99]
	v_lshl_add_u64 v[98:99], v[98:99], 0, s[42:43]
	global_store_dword v[98:99], v96, off
.LBB0_2989:
	s_or_b64 exec, exec, s[46:47]
	v_or_b32_e32 v96, 32, v140
	s_waitcnt lgkmcnt(0)
	v_ashrrev_i32_e32 v97, 31, v96
	v_lshlrev_b64 v[98:99], 10, v[96:97]
	v_readlane_b32 s46, v254, 6
	v_lshl_add_u64 v[98:99], v[98:99], 0, v[138:139]
	v_readlane_b32 s47, v254, 7
	s_and_b64 vcc, exec, s[4:5]
	s_nop 0
	v_lshl_add_u64 v[100:101], v[98:99], 1, s[46:47]
	s_waitcnt lgkmcnt(0)
	v_lshlrev_b32_e32 v106, 16, v202
	v_and_b32_e32 v107, 0xffff0000, v202
	v_lshlrev_b32_e32 v102, 16, v203
	v_and_b32_e32 v103, 0xffff0000, v203
	v_pk_add_f32 v[94:95], v[94:95], v[102:103]
	v_lshlrev_b32_e32 v102, 16, v204
	v_and_b32_e32 v103, 0xffff0000, v204
	v_pk_add_f32 v[88:89], v[88:89], v[102:103]
	v_lshlrev_b32_e32 v102, 16, v205
	v_and_b32_e32 v103, 0xffff0000, v205
	v_pk_add_f32 v[92:93], v[92:93], v[106:107]
	v_pk_add_f32 v[90:91], v[90:91], v[102:103]
	s_cbranch_vccnz .LBB0_2993
	s_and_b64 vcc, exec, s[6:7]
	s_cbranch_vccnz .LBB0_2992
	v_lshl_add_u64 v[102:103], v[98:99], 2, s[44:45]
	global_store_dwordx4 v[102:103], v[92:95], off
	global_store_dwordx4 v[102:103], v[88:91], off offset:16
.LBB0_2992:
	v_cvt_pk_bf16_f32 v102, v92, v93
	v_cvt_pk_bf16_f32 v103, v94, v95
	v_cvt_pk_bf16_f32 v104, v88, v89
	v_cvt_pk_bf16_f32 v105, v90, v91
	global_store_dwordx4 v[100:101], v[102:105], off
.LBB0_2993:
	v_lshlrev_b64 v[100:101], 1, v[98:99]
	v_readlane_b32 s46, v254, 6
	v_or_b32_e32 v100, 0x100, v100
	v_readlane_b32 s47, v254, 7
	s_and_b64 vcc, exec, s[4:5]
	s_nop 0
	v_lshl_add_u64 v[100:101], s[46:47], 0, v[100:101]
	s_waitcnt lgkmcnt(0)
	v_lshlrev_b32_e32 v106, 16, v206
	v_and_b32_e32 v107, 0xffff0000, v206
	v_lshlrev_b32_e32 v102, 16, v207
	v_and_b32_e32 v103, 0xffff0000, v207
	v_pk_add_f32 v[86:87], v[86:87], v[102:103]
	v_lshlrev_b32_e32 v102, 16, v208
	v_and_b32_e32 v103, 0xffff0000, v208
	v_pk_add_f32 v[80:81], v[80:81], v[102:103]
	v_lshlrev_b32_e32 v102, 16, v209
	v_and_b32_e32 v103, 0xffff0000, v209
	v_pk_add_f32 v[84:85], v[84:85], v[106:107]
	v_pk_add_f32 v[82:83], v[82:83], v[102:103]
	s_cbranch_vccnz .LBB0_2997
	s_and_b64 vcc, exec, s[6:7]
	s_cbranch_vccnz .LBB0_2996
	v_lshl_add_u64 v[98:99], v[98:99], 2, s[44:45]
	global_store_dwordx4 v[98:99], v[84:87], off offset:512
	global_store_dwordx4 v[98:99], v[80:83], off offset:528
.LBB0_2996:
	v_cvt_pk_bf16_f32 v102, v84, v85
	v_cvt_pk_bf16_f32 v103, v86, v87
	v_cvt_pk_bf16_f32 v104, v80, v81
	v_cvt_pk_bf16_f32 v105, v82, v83
	global_store_dwordx4 v[100:101], v[102:105], off
.LBB0_2997:
	v_pk_mul_f32 v[84:85], v[84:85], v[84:85]
	v_pk_mul_f32 v[86:87], v[86:87], v[86:87]
	v_pk_mul_f32 v[80:81], v[80:81], v[80:81]
	v_add_f32_e32 v86, v86, v87
	v_add_f32_e32 v84, v84, v85
	v_pk_mul_f32 v[82:83], v[82:83], v[82:83]
	v_add_f32_e32 v84, v84, v86
	v_add_f32_e32 v80, v80, v81
	v_pk_mul_f32 v[92:93], v[92:93], v[92:93]
	v_pk_mul_f32 v[94:95], v[94:95], v[94:95]
	v_add_f32_e32 v80, v80, v84
	v_add_f32_e32 v81, v82, v83
	v_pk_mul_f32 v[88:89], v[88:89], v[88:89]
	v_add_f32_e32 v80, v81, v80
	v_add_f32_e32 v81, v94, v95
	v_add_f32_e32 v82, v92, v93
	v_pk_mul_f32 v[90:91], v[90:91], v[90:91]
	v_add_f32_e32 v81, v82, v81
	v_add_f32_e32 v82, v88, v89
	v_add_f32_e32 v81, v82, v81
	v_add_f32_e32 v82, v90, v91
	v_add_f32_e32 v81, v82, v81
	v_add_f32_e32 v80, v81, v80
	ds_bpermute_b32 v81, v156, v80
	s_waitcnt lgkmcnt(0)
	v_add_f32_e32 v80, v80, v81
	ds_bpermute_b32 v81, v157, v80
	s_and_saveexec_b64 s[46:47], s[28:29]
	s_cbranch_execz .LBB0_2999
	v_readlane_b32 s48, v254, 8
	v_lshlrev_b64 v[82:83], 6, v[96:97]
	v_readlane_b32 s49, v254, 9
	s_lshl_b32 s42, s18, 2
	s_waitcnt lgkmcnt(0)
	v_add_f32_e32 v80, v80, v81
	v_lshl_add_u64 v[82:83], s[48:49], 0, v[82:83]
	v_lshl_add_u64 v[82:83], s[56:57], 2, v[82:83]
	v_lshl_add_u64 v[82:83], v[82:83], 0, s[42:43]
	global_store_dword v[82:83], v80, off
.LBB0_2999:
	s_or_b64 exec, exec, s[46:47]
	v_or_b32_e32 v80, 48, v140
	s_waitcnt lgkmcnt(0)
	v_ashrrev_i32_e32 v81, 31, v80
	v_lshlrev_b64 v[82:83], 10, v[80:81]
	v_readlane_b32 s46, v254, 6
	v_lshl_add_u64 v[82:83], v[82:83], 0, v[138:139]
	v_readlane_b32 s47, v254, 7
	s_and_b64 vcc, exec, s[4:5]
	s_nop 0
	v_lshl_add_u64 v[84:85], v[82:83], 1, s[46:47]
	s_waitcnt lgkmcnt(0)
	v_lshlrev_b32_e32 v90, 16, v210
	v_and_b32_e32 v91, 0xffff0000, v210
	v_lshlrev_b32_e32 v86, 16, v211
	v_and_b32_e32 v87, 0xffff0000, v211
	v_pk_add_f32 v[78:79], v[78:79], v[86:87]
	v_lshlrev_b32_e32 v86, 16, v212
	v_and_b32_e32 v87, 0xffff0000, v212
	v_pk_add_f32 v[72:73], v[72:73], v[86:87]
	v_lshlrev_b32_e32 v86, 16, v213
	v_and_b32_e32 v87, 0xffff0000, v213
	v_pk_add_f32 v[76:77], v[76:77], v[90:91]
	v_pk_add_f32 v[74:75], v[74:75], v[86:87]
	s_cbranch_vccnz .LBB0_3003
	s_and_b64 vcc, exec, s[6:7]
	s_cbranch_vccnz .LBB0_3002
	v_lshl_add_u64 v[86:87], v[82:83], 2, s[44:45]
	global_store_dwordx4 v[86:87], v[76:79], off
	global_store_dwordx4 v[86:87], v[72:75], off offset:16
.LBB0_3002:
	v_cvt_pk_bf16_f32 v86, v76, v77
	v_cvt_pk_bf16_f32 v87, v78, v79
	v_cvt_pk_bf16_f32 v88, v72, v73
	v_cvt_pk_bf16_f32 v89, v74, v75
	global_store_dwordx4 v[84:85], v[86:89], off
.LBB0_3003:
	v_lshlrev_b64 v[84:85], 1, v[82:83]
	v_readlane_b32 s46, v254, 6
	v_or_b32_e32 v84, 0x100, v84
	v_readlane_b32 s47, v254, 7
	s_and_b64 vcc, exec, s[4:5]
	s_nop 0
	v_lshl_add_u64 v[84:85], s[46:47], 0, v[84:85]
	s_waitcnt lgkmcnt(0)
	v_lshlrev_b32_e32 v90, 16, v214
	v_and_b32_e32 v91, 0xffff0000, v214
	v_lshlrev_b32_e32 v86, 16, v215
	v_and_b32_e32 v87, 0xffff0000, v215
	v_pk_add_f32 v[70:71], v[70:71], v[86:87]
	v_lshlrev_b32_e32 v86, 16, v216
	v_and_b32_e32 v87, 0xffff0000, v216
	v_pk_add_f32 v[64:65], v[64:65], v[86:87]
	v_lshlrev_b32_e32 v86, 16, v217
	v_and_b32_e32 v87, 0xffff0000, v217
	v_pk_add_f32 v[68:69], v[68:69], v[90:91]
	v_pk_add_f32 v[66:67], v[66:67], v[86:87]
	s_cbranch_vccnz .LBB0_3007
	s_and_b64 vcc, exec, s[6:7]
	s_cbranch_vccnz .LBB0_3006
	v_lshl_add_u64 v[82:83], v[82:83], 2, s[44:45]
	global_store_dwordx4 v[82:83], v[68:71], off offset:512
	global_store_dwordx4 v[82:83], v[64:67], off offset:528
.LBB0_3006:
	v_cvt_pk_bf16_f32 v86, v68, v69
	v_cvt_pk_bf16_f32 v87, v70, v71
	v_cvt_pk_bf16_f32 v88, v64, v65
	v_cvt_pk_bf16_f32 v89, v66, v67
	global_store_dwordx4 v[84:85], v[86:89], off
.LBB0_3007:
	v_pk_mul_f32 v[68:69], v[68:69], v[68:69]
	v_pk_mul_f32 v[70:71], v[70:71], v[70:71]
	v_pk_mul_f32 v[64:65], v[64:65], v[64:65]
	v_add_f32_e32 v70, v70, v71
	v_add_f32_e32 v68, v68, v69
	v_pk_mul_f32 v[66:67], v[66:67], v[66:67]
	v_add_f32_e32 v68, v68, v70
	v_add_f32_e32 v64, v64, v65
	v_pk_mul_f32 v[76:77], v[76:77], v[76:77]
	v_pk_mul_f32 v[78:79], v[78:79], v[78:79]
	v_add_f32_e32 v64, v64, v68
	v_add_f32_e32 v65, v66, v67
	v_pk_mul_f32 v[72:73], v[72:73], v[72:73]
	v_add_f32_e32 v64, v65, v64
	v_add_f32_e32 v65, v78, v79
	v_add_f32_e32 v66, v76, v77
	v_pk_mul_f32 v[74:75], v[74:75], v[74:75]
	v_add_f32_e32 v65, v66, v65
	v_add_f32_e32 v66, v72, v73
	v_add_f32_e32 v65, v66, v65
	v_add_f32_e32 v66, v74, v75
	v_add_f32_e32 v65, v66, v65
	v_add_f32_e32 v64, v65, v64
	ds_bpermute_b32 v65, v156, v64
	s_waitcnt lgkmcnt(0)
	v_add_f32_e32 v64, v64, v65
	ds_bpermute_b32 v65, v157, v64
	s_and_saveexec_b64 s[46:47], s[28:29]
	s_cbranch_execz .LBB0_3009
	v_readlane_b32 s48, v254, 8
	v_lshlrev_b64 v[66:67], 6, v[80:81]
	v_readlane_b32 s49, v254, 9
	s_lshl_b32 s42, s18, 2
	s_waitcnt lgkmcnt(0)
	v_add_f32_e32 v64, v64, v65
	v_lshl_add_u64 v[66:67], s[48:49], 0, v[66:67]
	v_lshl_add_u64 v[66:67], s[56:57], 2, v[66:67]
	v_lshl_add_u64 v[66:67], v[66:67], 0, s[42:43]
	global_store_dword v[66:67], v64, off
.LBB0_3009:
	s_or_b64 exec, exec, s[46:47]
	v_add_u32_e32 v64, 0x80, v140
	s_waitcnt lgkmcnt(0)
	v_ashrrev_i32_e32 v65, 31, v64
	v_lshlrev_b64 v[66:67], 10, v[64:65]
	v_readlane_b32 s46, v254, 6
	v_lshl_add_u64 v[66:67], v[66:67], 0, v[138:139]
	v_readlane_b32 s47, v254, 7
	s_and_b64 vcc, exec, s[4:5]
	s_nop 0
	v_lshl_add_u64 v[68:69], v[66:67], 1, s[46:47]
	v_add_u32_e32 v234, 160, v140
	v_ashrrev_i32_e32 v235, 31, v234
	v_lshlrev_b64 v[234:235], 11, v[234:235]
	v_lshl_add_u64 v[234:235], s[46:47], 0, v[234:235]
	v_lshl_add_u64 v[234:235], v[138:139], 1, v[234:235]
	global_load_dwordx4 v[186:189], v[234:235], off
	global_load_dwordx4 v[190:193], v[234:235], off offset:256
	v_add_u32_e32 v234, 176, v140
	v_ashrrev_i32_e32 v235, 31, v234
	v_lshlrev_b64 v[234:235], 11, v[234:235]
	v_lshl_add_u64 v[234:235], s[46:47], 0, v[234:235]
	v_lshl_add_u64 v[234:235], v[138:139], 1, v[234:235]
	global_load_dwordx4 v[194:197], v[234:235], off
	global_load_dwordx4 v[198:201], v[234:235], off offset:256
	s_waitcnt lgkmcnt(0)
	v_lshlrev_b32_e32 v74, 16, v218
	v_and_b32_e32 v75, 0xffff0000, v218
	v_lshlrev_b32_e32 v70, 16, v219
	v_and_b32_e32 v71, 0xffff0000, v219
	v_pk_add_f32 v[62:63], v[62:63], v[70:71]
	v_lshlrev_b32_e32 v70, 16, v220
	v_and_b32_e32 v71, 0xffff0000, v220
	v_pk_add_f32 v[56:57], v[56:57], v[70:71]
	v_lshlrev_b32_e32 v70, 16, v221
	v_and_b32_e32 v71, 0xffff0000, v221
	v_pk_add_f32 v[60:61], v[60:61], v[74:75]
	v_pk_add_f32 v[58:59], v[58:59], v[70:71]
	s_cbranch_vccnz .LBB0_3013
	s_and_b64 vcc, exec, s[6:7]
	s_cbranch_vccnz .LBB0_3012
	v_lshl_add_u64 v[70:71], v[66:67], 2, s[44:45]
	global_store_dwordx4 v[70:71], v[60:63], off
	global_store_dwordx4 v[70:71], v[56:59], off offset:16
.LBB0_3012:
	v_cvt_pk_bf16_f32 v70, v60, v61
	v_cvt_pk_bf16_f32 v71, v62, v63
	v_cvt_pk_bf16_f32 v72, v56, v57
	v_cvt_pk_bf16_f32 v73, v58, v59
	global_store_dwordx4 v[68:69], v[70:73], off
.LBB0_3013:
	v_lshlrev_b64 v[68:69], 1, v[66:67]
	v_readlane_b32 s46, v254, 6
	v_or_b32_e32 v68, 0x100, v68
	v_readlane_b32 s47, v254, 7
	s_and_b64 vcc, exec, s[4:5]
	s_nop 0
	v_lshl_add_u64 v[68:69], s[46:47], 0, v[68:69]
	s_waitcnt lgkmcnt(0)
	v_lshlrev_b32_e32 v74, 16, v222
	v_and_b32_e32 v75, 0xffff0000, v222
	v_lshlrev_b32_e32 v70, 16, v223
	v_and_b32_e32 v71, 0xffff0000, v223
	v_pk_add_f32 v[54:55], v[54:55], v[70:71]
	v_lshlrev_b32_e32 v70, 16, v224
	v_and_b32_e32 v71, 0xffff0000, v224
	v_pk_add_f32 v[48:49], v[48:49], v[70:71]
	v_lshlrev_b32_e32 v70, 16, v225
	v_and_b32_e32 v71, 0xffff0000, v225
	v_pk_add_f32 v[52:53], v[52:53], v[74:75]
	v_pk_add_f32 v[50:51], v[50:51], v[70:71]
	s_cbranch_vccnz .LBB0_3017
	s_and_b64 vcc, exec, s[6:7]
	s_cbranch_vccnz .LBB0_3016
	v_lshl_add_u64 v[66:67], v[66:67], 2, s[44:45]
	global_store_dwordx4 v[66:67], v[52:55], off offset:512
	global_store_dwordx4 v[66:67], v[48:51], off offset:528
.LBB0_3016:
	v_cvt_pk_bf16_f32 v70, v52, v53
	v_cvt_pk_bf16_f32 v71, v54, v55
	v_cvt_pk_bf16_f32 v72, v48, v49
	v_cvt_pk_bf16_f32 v73, v50, v51
	global_store_dwordx4 v[68:69], v[70:73], off
.LBB0_3017:
	v_pk_mul_f32 v[52:53], v[52:53], v[52:53]
	v_pk_mul_f32 v[54:55], v[54:55], v[54:55]
	v_pk_mul_f32 v[48:49], v[48:49], v[48:49]
	v_add_f32_e32 v54, v54, v55
	v_add_f32_e32 v52, v52, v53
	v_pk_mul_f32 v[50:51], v[50:51], v[50:51]
	v_add_f32_e32 v52, v52, v54
	v_add_f32_e32 v48, v48, v49
	v_pk_mul_f32 v[60:61], v[60:61], v[60:61]
	v_pk_mul_f32 v[62:63], v[62:63], v[62:63]
	v_add_f32_e32 v48, v48, v52
	v_add_f32_e32 v49, v50, v51
	v_pk_mul_f32 v[56:57], v[56:57], v[56:57]
	v_add_f32_e32 v48, v49, v48
	v_add_f32_e32 v49, v62, v63
	v_add_f32_e32 v50, v60, v61
	v_pk_mul_f32 v[58:59], v[58:59], v[58:59]
	v_add_f32_e32 v49, v50, v49
	v_add_f32_e32 v50, v56, v57
	v_add_f32_e32 v49, v50, v49
	v_add_f32_e32 v50, v58, v59
	v_add_f32_e32 v49, v50, v49
	v_add_f32_e32 v48, v49, v48
	ds_bpermute_b32 v49, v156, v48
	s_waitcnt lgkmcnt(0)
	v_add_f32_e32 v48, v48, v49
	ds_bpermute_b32 v49, v157, v48
	s_and_saveexec_b64 s[46:47], s[28:29]
	s_cbranch_execz .LBB0_3019
	v_readlane_b32 s48, v254, 8
	v_lshlrev_b64 v[50:51], 6, v[64:65]
	v_readlane_b32 s49, v254, 9
	s_lshl_b32 s42, s18, 2
	s_waitcnt lgkmcnt(0)
	v_add_f32_e32 v48, v48, v49
	v_lshl_add_u64 v[50:51], s[48:49], 0, v[50:51]
	v_lshl_add_u64 v[50:51], s[56:57], 2, v[50:51]
	v_lshl_add_u64 v[50:51], v[50:51], 0, s[42:43]
	global_store_dword v[50:51], v48, off
.LBB0_3019:
	s_or_b64 exec, exec, s[46:47]
	v_add_u32_e32 v48, 0x90, v140
	s_waitcnt lgkmcnt(0)
	v_ashrrev_i32_e32 v49, 31, v48
	v_lshlrev_b64 v[50:51], 10, v[48:49]
	v_readlane_b32 s46, v254, 6
	v_lshl_add_u64 v[50:51], v[50:51], 0, v[138:139]
	v_readlane_b32 s47, v254, 7
	s_and_b64 vcc, exec, s[4:5]
	s_nop 0
	v_lshl_add_u64 v[52:53], v[50:51], 1, s[46:47]
	s_waitcnt lgkmcnt(0)
	v_lshlrev_b32_e32 v58, 16, v226
	v_and_b32_e32 v59, 0xffff0000, v226
	v_lshlrev_b32_e32 v54, 16, v227
	v_and_b32_e32 v55, 0xffff0000, v227
	v_pk_add_f32 v[46:47], v[46:47], v[54:55]
	v_lshlrev_b32_e32 v54, 16, v228
	v_and_b32_e32 v55, 0xffff0000, v228
	v_pk_add_f32 v[40:41], v[40:41], v[54:55]
	v_lshlrev_b32_e32 v54, 16, v229
	v_and_b32_e32 v55, 0xffff0000, v229
	v_pk_add_f32 v[44:45], v[44:45], v[58:59]
	v_pk_add_f32 v[42:43], v[42:43], v[54:55]
	s_cbranch_vccnz .LBB0_3023
	s_and_b64 vcc, exec, s[6:7]
	s_cbranch_vccnz .LBB0_3022
	v_lshl_add_u64 v[54:55], v[50:51], 2, s[44:45]
	global_store_dwordx4 v[54:55], v[44:47], off
	global_store_dwordx4 v[54:55], v[40:43], off offset:16
.LBB0_3022:
	v_cvt_pk_bf16_f32 v54, v44, v45
	v_cvt_pk_bf16_f32 v55, v46, v47
	v_cvt_pk_bf16_f32 v56, v40, v41
	v_cvt_pk_bf16_f32 v57, v42, v43
	global_store_dwordx4 v[52:53], v[54:57], off
.LBB0_3023:
	v_lshlrev_b64 v[52:53], 1, v[50:51]
	v_readlane_b32 s46, v254, 6
	v_or_b32_e32 v52, 0x100, v52
	v_readlane_b32 s47, v254, 7
	s_and_b64 vcc, exec, s[4:5]
	s_nop 0
	v_lshl_add_u64 v[52:53], s[46:47], 0, v[52:53]
	s_waitcnt lgkmcnt(0)
	v_lshlrev_b32_e32 v58, 16, v230
	v_and_b32_e32 v59, 0xffff0000, v230
	v_lshlrev_b32_e32 v54, 16, v231
	v_and_b32_e32 v55, 0xffff0000, v231
	v_pk_add_f32 v[38:39], v[38:39], v[54:55]
	v_lshlrev_b32_e32 v54, 16, v232
	v_and_b32_e32 v55, 0xffff0000, v232
	v_pk_add_f32 v[32:33], v[32:33], v[54:55]
	v_lshlrev_b32_e32 v54, 16, v233
	v_and_b32_e32 v55, 0xffff0000, v233
	v_pk_add_f32 v[36:37], v[36:37], v[58:59]
	v_pk_add_f32 v[34:35], v[34:35], v[54:55]
	s_cbranch_vccnz .LBB0_3027
	s_and_b64 vcc, exec, s[6:7]
	s_cbranch_vccnz .LBB0_3026
	v_lshl_add_u64 v[50:51], v[50:51], 2, s[44:45]
	global_store_dwordx4 v[50:51], v[36:39], off offset:512
	global_store_dwordx4 v[50:51], v[32:35], off offset:528
.LBB0_3026:
	v_cvt_pk_bf16_f32 v54, v36, v37
	v_cvt_pk_bf16_f32 v55, v38, v39
	v_cvt_pk_bf16_f32 v56, v32, v33
	v_cvt_pk_bf16_f32 v57, v34, v35
	global_store_dwordx4 v[52:53], v[54:57], off
.LBB0_3027:
	v_pk_mul_f32 v[36:37], v[36:37], v[36:37]
	v_pk_mul_f32 v[38:39], v[38:39], v[38:39]
	v_pk_mul_f32 v[32:33], v[32:33], v[32:33]
	v_add_f32_e32 v38, v38, v39
	v_add_f32_e32 v36, v36, v37
	v_pk_mul_f32 v[34:35], v[34:35], v[34:35]
	v_add_f32_e32 v36, v36, v38
	v_add_f32_e32 v32, v32, v33
	v_pk_mul_f32 v[44:45], v[44:45], v[44:45]
	v_pk_mul_f32 v[46:47], v[46:47], v[46:47]
	v_add_f32_e32 v32, v32, v36
	v_add_f32_e32 v33, v34, v35
	v_pk_mul_f32 v[40:41], v[40:41], v[40:41]
	v_add_f32_e32 v32, v33, v32
	v_add_f32_e32 v33, v46, v47
	v_add_f32_e32 v34, v44, v45
	v_pk_mul_f32 v[42:43], v[42:43], v[42:43]
	v_add_f32_e32 v33, v34, v33
	v_add_f32_e32 v34, v40, v41
	v_add_f32_e32 v33, v34, v33
	v_add_f32_e32 v34, v42, v43
	v_add_f32_e32 v33, v34, v33
	v_add_f32_e32 v32, v33, v32
	ds_bpermute_b32 v33, v156, v32
	s_waitcnt lgkmcnt(0)
	v_add_f32_e32 v32, v32, v33
	ds_bpermute_b32 v33, v157, v32
	s_and_saveexec_b64 s[46:47], s[28:29]
	s_cbranch_execz .LBB0_3029
	v_readlane_b32 s48, v254, 8
	v_lshlrev_b64 v[34:35], 6, v[48:49]
	v_readlane_b32 s49, v254, 9
	s_lshl_b32 s42, s18, 2
	s_waitcnt lgkmcnt(0)
	v_add_f32_e32 v32, v32, v33
	v_lshl_add_u64 v[34:35], s[48:49], 0, v[34:35]
	v_lshl_add_u64 v[34:35], s[56:57], 2, v[34:35]
	v_lshl_add_u64 v[34:35], v[34:35], 0, s[42:43]
	global_store_dword v[34:35], v32, off
.LBB0_3029:
	s_or_b64 exec, exec, s[46:47]
	v_add_u32_e32 v32, 0xa0, v140
	s_waitcnt lgkmcnt(0)
	v_ashrrev_i32_e32 v33, 31, v32
	v_lshlrev_b64 v[34:35], 10, v[32:33]
	v_readlane_b32 s46, v254, 6
	v_lshl_add_u64 v[34:35], v[34:35], 0, v[138:139]
	v_readlane_b32 s47, v254, 7
	s_and_b64 vcc, exec, s[4:5]
	s_nop 0
	v_lshl_add_u64 v[36:37], v[34:35], 1, s[46:47]
	s_waitcnt vmcnt(0)
	s_waitcnt lgkmcnt(0)
	v_lshlrev_b32_e32 v42, 16, v186
	v_and_b32_e32 v43, 0xffff0000, v186
	v_lshlrev_b32_e32 v38, 16, v187
	v_and_b32_e32 v39, 0xffff0000, v187
	v_pk_add_f32 v[30:31], v[30:31], v[38:39]
	v_lshlrev_b32_e32 v38, 16, v188
	v_and_b32_e32 v39, 0xffff0000, v188
	v_pk_add_f32 v[24:25], v[24:25], v[38:39]
	v_lshlrev_b32_e32 v38, 16, v189
	v_and_b32_e32 v39, 0xffff0000, v189
	v_pk_add_f32 v[28:29], v[28:29], v[42:43]
	v_pk_add_f32 v[26:27], v[26:27], v[38:39]
	s_cbranch_vccnz .LBB0_3033
	s_and_b64 vcc, exec, s[6:7]
	s_cbranch_vccnz .LBB0_3032
	v_lshl_add_u64 v[38:39], v[34:35], 2, s[44:45]
	global_store_dwordx4 v[38:39], v[28:31], off
	global_store_dwordx4 v[38:39], v[24:27], off offset:16
.LBB0_3032:
	v_cvt_pk_bf16_f32 v38, v28, v29
	v_cvt_pk_bf16_f32 v39, v30, v31
	v_cvt_pk_bf16_f32 v40, v24, v25
	v_cvt_pk_bf16_f32 v41, v26, v27
	global_store_dwordx4 v[36:37], v[38:41], off
.LBB0_3033:
	v_lshlrev_b64 v[36:37], 1, v[34:35]
	v_readlane_b32 s46, v254, 6
	v_or_b32_e32 v36, 0x100, v36
	v_readlane_b32 s47, v254, 7
	s_and_b64 vcc, exec, s[4:5]
	s_nop 0
	v_lshl_add_u64 v[36:37], s[46:47], 0, v[36:37]
	s_waitcnt lgkmcnt(0)
	v_lshlrev_b32_e32 v42, 16, v190
	v_and_b32_e32 v43, 0xffff0000, v190
	v_lshlrev_b32_e32 v38, 16, v191
	v_and_b32_e32 v39, 0xffff0000, v191
	v_pk_add_f32 v[22:23], v[22:23], v[38:39]
	v_lshlrev_b32_e32 v38, 16, v192
	v_and_b32_e32 v39, 0xffff0000, v192
	v_pk_add_f32 v[16:17], v[16:17], v[38:39]
	v_lshlrev_b32_e32 v38, 16, v193
	v_and_b32_e32 v39, 0xffff0000, v193
	v_pk_add_f32 v[20:21], v[20:21], v[42:43]
	v_pk_add_f32 v[18:19], v[18:19], v[38:39]
	s_cbranch_vccnz .LBB0_3037
	s_and_b64 vcc, exec, s[6:7]
	s_cbranch_vccnz .LBB0_3036
	v_lshl_add_u64 v[34:35], v[34:35], 2, s[44:45]
	global_store_dwordx4 v[34:35], v[20:23], off offset:512
	global_store_dwordx4 v[34:35], v[16:19], off offset:528
.LBB0_3036:
	v_cvt_pk_bf16_f32 v38, v20, v21
	v_cvt_pk_bf16_f32 v39, v22, v23
	v_cvt_pk_bf16_f32 v40, v16, v17
	v_cvt_pk_bf16_f32 v41, v18, v19
	global_store_dwordx4 v[36:37], v[38:41], off
.LBB0_3037:
	v_pk_mul_f32 v[20:21], v[20:21], v[20:21]
	v_pk_mul_f32 v[22:23], v[22:23], v[22:23]
	v_pk_mul_f32 v[16:17], v[16:17], v[16:17]
	v_add_f32_e32 v22, v22, v23
	v_add_f32_e32 v20, v20, v21
	v_pk_mul_f32 v[18:19], v[18:19], v[18:19]
	v_add_f32_e32 v20, v20, v22
	v_add_f32_e32 v16, v16, v17
	v_pk_mul_f32 v[28:29], v[28:29], v[28:29]
	v_pk_mul_f32 v[30:31], v[30:31], v[30:31]
	v_add_f32_e32 v16, v16, v20
	v_add_f32_e32 v17, v18, v19
	v_pk_mul_f32 v[24:25], v[24:25], v[24:25]
	v_add_f32_e32 v16, v17, v16
	v_add_f32_e32 v17, v30, v31
	v_add_f32_e32 v18, v28, v29
	v_pk_mul_f32 v[26:27], v[26:27], v[26:27]
	v_add_f32_e32 v17, v18, v17
	v_add_f32_e32 v18, v24, v25
	v_add_f32_e32 v17, v18, v17
	v_add_f32_e32 v18, v26, v27
	v_add_f32_e32 v17, v18, v17
	v_add_f32_e32 v16, v17, v16
	ds_bpermute_b32 v17, v156, v16
	s_waitcnt lgkmcnt(0)
	v_add_f32_e32 v16, v16, v17
	ds_bpermute_b32 v17, v157, v16
	s_and_saveexec_b64 s[46:47], s[28:29]
	s_cbranch_execz .LBB0_3039
	v_readlane_b32 s48, v254, 8
	v_lshlrev_b64 v[18:19], 6, v[32:33]
	v_readlane_b32 s49, v254, 9
	s_lshl_b32 s42, s18, 2
	s_waitcnt lgkmcnt(0)
	v_add_f32_e32 v16, v16, v17
	v_lshl_add_u64 v[18:19], s[48:49], 0, v[18:19]
	v_lshl_add_u64 v[18:19], s[56:57], 2, v[18:19]
	v_lshl_add_u64 v[18:19], v[18:19], 0, s[42:43]
	global_store_dword v[18:19], v16, off
.LBB0_3039:
	s_or_b64 exec, exec, s[46:47]
	v_add_u32_e32 v16, 0xb0, v140
	s_waitcnt lgkmcnt(0)
	v_ashrrev_i32_e32 v17, 31, v16
	v_lshlrev_b64 v[18:19], 10, v[16:17]
	v_readlane_b32 s46, v254, 6
	v_lshl_add_u64 v[18:19], v[18:19], 0, v[138:139]
	v_readlane_b32 s47, v254, 7
	s_and_b64 vcc, exec, s[4:5]
	s_nop 0
	v_lshl_add_u64 v[20:21], v[18:19], 1, s[46:47]
	s_waitcnt lgkmcnt(0)
	v_lshlrev_b32_e32 v26, 16, v194
	v_and_b32_e32 v27, 0xffff0000, v194
	v_lshlrev_b32_e32 v22, 16, v195
	v_and_b32_e32 v23, 0xffff0000, v195
	v_pk_add_f32 v[14:15], v[14:15], v[22:23]
	v_lshlrev_b32_e32 v22, 16, v196
	v_and_b32_e32 v23, 0xffff0000, v196
	v_pk_add_f32 v[8:9], v[8:9], v[22:23]
	v_lshlrev_b32_e32 v22, 16, v197
	v_and_b32_e32 v23, 0xffff0000, v197
	v_pk_add_f32 v[12:13], v[12:13], v[26:27]
	v_pk_add_f32 v[10:11], v[10:11], v[22:23]
	s_cbranch_vccnz .LBB0_3043
	s_and_b64 vcc, exec, s[6:7]
	s_cbranch_vccnz .LBB0_3042
	v_lshl_add_u64 v[22:23], v[18:19], 2, s[44:45]
	global_store_dwordx4 v[22:23], v[12:15], off
	global_store_dwordx4 v[22:23], v[8:11], off offset:16
.LBB0_3042:
	v_cvt_pk_bf16_f32 v22, v12, v13
	v_cvt_pk_bf16_f32 v23, v14, v15
	v_cvt_pk_bf16_f32 v24, v8, v9
	v_cvt_pk_bf16_f32 v25, v10, v11
	global_store_dwordx4 v[20:21], v[22:25], off
.LBB0_3043:
	v_lshlrev_b64 v[20:21], 1, v[18:19]
	v_readlane_b32 s46, v254, 6
	v_or_b32_e32 v20, 0x100, v20
	v_readlane_b32 s47, v254, 7
	s_and_b64 vcc, exec, s[4:5]
	s_nop 0
	v_lshl_add_u64 v[20:21], s[46:47], 0, v[20:21]
	s_waitcnt lgkmcnt(0)
	v_lshlrev_b32_e32 v26, 16, v198
	v_and_b32_e32 v27, 0xffff0000, v198
	v_lshlrev_b32_e32 v22, 16, v199
	v_and_b32_e32 v23, 0xffff0000, v199
	v_pk_add_f32 v[6:7], v[6:7], v[22:23]
	v_lshlrev_b32_e32 v22, 16, v200
	v_and_b32_e32 v23, 0xffff0000, v200
	v_pk_add_f32 v[0:1], v[0:1], v[22:23]
	v_lshlrev_b32_e32 v22, 16, v201
	v_and_b32_e32 v23, 0xffff0000, v201
	v_pk_add_f32 v[4:5], v[4:5], v[26:27]
	v_pk_add_f32 v[2:3], v[2:3], v[22:23]
	s_cbranch_vccnz .LBB0_3047
	s_and_b64 vcc, exec, s[6:7]
	s_cbranch_vccnz .LBB0_3046
	v_lshl_add_u64 v[18:19], v[18:19], 2, s[44:45]
	global_store_dwordx4 v[18:19], v[4:7], off offset:512
	global_store_dwordx4 v[18:19], v[0:3], off offset:528
.LBB0_3046:
	v_cvt_pk_bf16_f32 v22, v4, v5
	v_cvt_pk_bf16_f32 v23, v6, v7
	v_cvt_pk_bf16_f32 v24, v0, v1
	v_cvt_pk_bf16_f32 v25, v2, v3
	global_store_dwordx4 v[20:21], v[22:25], off
.LBB0_3047:
	v_pk_mul_f32 v[4:5], v[4:5], v[4:5]
	v_pk_mul_f32 v[6:7], v[6:7], v[6:7]
	v_pk_mul_f32 v[0:1], v[0:1], v[0:1]
	v_add_f32_e32 v6, v6, v7
	v_add_f32_e32 v4, v4, v5
	v_pk_mul_f32 v[2:3], v[2:3], v[2:3]
	v_add_f32_e32 v4, v4, v6
	v_add_f32_e32 v0, v0, v1
	v_pk_mul_f32 v[12:13], v[12:13], v[12:13]
	v_pk_mul_f32 v[14:15], v[14:15], v[14:15]
	v_add_f32_e32 v0, v0, v4
	v_add_f32_e32 v1, v2, v3
	v_pk_mul_f32 v[8:9], v[8:9], v[8:9]
	v_add_f32_e32 v0, v1, v0
	v_add_f32_e32 v1, v14, v15
	v_add_f32_e32 v2, v12, v13
	v_pk_mul_f32 v[10:11], v[10:11], v[10:11]
	v_add_f32_e32 v1, v2, v1
	v_add_f32_e32 v2, v8, v9
	v_add_f32_e32 v1, v2, v1
	v_add_f32_e32 v2, v10, v11
	v_add_f32_e32 v1, v2, v1
	v_add_f32_e32 v0, v1, v0
	ds_bpermute_b32 v1, v156, v0
	s_waitcnt lgkmcnt(0)
	v_add_f32_e32 v0, v0, v1
	ds_bpermute_b32 v1, v157, v0
	s_and_saveexec_b64 s[4:5], s[28:29]
	s_cbranch_execz .LBB0_3049
	v_readlane_b32 s6, v254, 8
	v_lshlrev_b64 v[2:3], 6, v[16:17]
	v_readlane_b32 s7, v254, 9
	s_lshl_b32 s42, s18, 2
	s_waitcnt lgkmcnt(0)
	v_add_f32_e32 v0, v0, v1
	v_lshl_add_u64 v[2:3], s[6:7], 0, v[2:3]
	v_lshl_add_u64 v[2:3], s[56:57], 2, v[2:3]
	v_lshl_add_u64 v[2:3], v[2:3], 0, s[42:43]
	global_store_dword v[2:3], v0, off
